# S5-Y k-loop: A operand on 3-slot LDS ring (LDS 160KB, barrier state moved to VGPRs), A(k+2) prefetch with counted vmcnt(4)
# speedup vs baseline: 1.0031x; 1.0031x over previous
; #define LAS __attribute__((address_space(3)))
; __global__ void __launch_bounds__(512, 1) fwd_megakernel(Params p) {
;   __shared__ __attribute__((aligned(16))) char lds_all[LDS_BYTES];
;     ...
;   cg::grid_group grid = cg::this_grid();
;   __shared__ uint4 xb_words;
;   if (threadIdx.x == 0) xb_words = make_uint4(0u, 0u, 0u, 0u);
;   __syncthreads();
;   { Params q; load_params(q); (void)xcd_barrier_post((unsigned*)(q.ws + W_BAR), (volatile LAS unsigned*)&xb_words); }
_Z14fwd_megakernel6Params:
	s_load_dwordx2 s[4:5], s[0:1], 0x100
	v_and_b32_e32 v182, 0x3ff, v0
	v_writelane_b32 v251, s2, 0
	s_add_u32 s2, s0, 0x100
	s_mov_b32 s6, 0
	s_waitcnt lgkmcnt(0)
	v_writelane_b32 v251, s4, 1
	s_nop 1
	v_writelane_b32 v251, s5, 2
	v_writelane_b32 v251, s0, 3
	s_addc_u32 s3, s1, 0
	v_cmp_eq_u32_e64 s[4:5], 0, v182
	v_writelane_b32 v251, s1, 4
	s_mov_b64 s[0:1], exec
	v_writelane_b32 v251, s4, 5
	s_nop 1
	v_writelane_b32 v251, s5, 6
	s_and_b64 s[4:5], s[0:1], s[4:5]
	s_mov_b64 exec, s[4:5]
	s_cbranch_execz .LBB0_2
	v_mov_b32_e32 v2, 0
	v_mov_b32_e32 v3, v2
	v_mov_b32_e32 v4, v2
	v_mov_b32_e32 v5, v2
	v_mov_b32_e32 v1, 0x20800
	v_mov_b32_e32 v252, 0
	v_mov_b32_e32 v253, 0

; DI unsigned xb_ld(unsigned* p) { return __hip_atomic_load(p, __ATOMIC_RELAXED, __HIP_MEMORY_SCOPE_AGENT); }
; DI void xcd_barrier_complete(unsigned* bar, unsigned x, unsigned& nloc, unsigned& nx) {
;   const unsigned G = gridDim.x * gridDim.y * gridDim.z;
;   unsigned sum, cnt, mine, sp = 0u;
;   for (;;) {
;     sum = 0u; cnt = 0u; mine = 0u;
; #pragma unroll
;     for (unsigned j = 0; j < 16; ++j) { const unsigned c = xb_ld(&bar[XB_XCNT(j)]); sum += c; cnt += (c > 0u) ? 1u : 0u; mine = (j == x) ? c : mine; }
; DI void xcd_barrier(const XcdBarrier& b) {
;   asm volatile("s_waitcnt vmcnt(0)" ::: "memory");
;   __syncthreads();
;   if (threadIdx.x == 0) {
;     unsigned* bar = b.bar;
;     __builtin_amdgcn_s_waitcnt(0);
;     unsigned nloc = b.st[0], nx = b.st[1];
;     if (nloc == 0u) { xcd_barrier_complete(bar, b.x, nloc, nx); b.st[0] = nloc; b.st[1] = nx; }
.LBB0_80:
	v_readlane_b32 s0, v251, 3
	v_readlane_b32 s1, v251, 4
	s_load_dword s1, s[0:1], 0x108
	v_readlane_b32 s2, v251, 1
	v_readlane_b32 s3, v251, 2
	s_mov_b32 s0, 0
	s_mul_i32 s3, s3, s2
	s_getreg_b32 s2, hwreg(HW_REG_XCC_ID, 0, 4)
	s_waitcnt vmcnt(0)
	s_waitcnt lgkmcnt(0)
	s_mul_i32 s1, s3, s1
	v_writelane_b32 v251, s1, 9
	s_barrier
	s_mov_b64 s[4:5], exec
	v_readlane_b32 s6, v251, 5
	v_readlane_b32 s7, v251, 6
	s_and_b64 s[6:7], s[4:5], s[6:7]
	s_mov_b64 exec, s[6:7]
	s_cbranch_execz .LBB0_132
	s_ashr_i32 s1, s0, 31
	v_readlane_b32 s6, v251, 3
	v_readlane_b32 s7, v251, 4
	s_add_u32 s0, s6, s0
	s_addc_u32 s1, s7, s1
	v_mov_b32_e32 v0, 0x20800
	s_load_dwordx2 s[0:1], s[0:1], 0xf8
	s_waitcnt vmcnt(0) expcnt(0) lgkmcnt(0)
	v_mov_b32_e32 v2, v252
	v_mov_b32_e32 v0, 0x20804
	v_mov_b32_e32 v0, v253
	s_and_b32 s33, s2, 15
	s_waitcnt lgkmcnt(1)
	v_cmp_ne_u32_e32 vcc, 0, v2
	s_cbranch_vccnz .LBB0_96
	s_add_u32 s2, s0, 0x16a4300
	s_addc_u32 s3, s1, 0
	s_add_u32 s6, s0, 0x16a4500
	s_addc_u32 s7, s1, 0
	s_add_u32 s8, s0, 0x16a4600
	s_addc_u32 s9, s1, 0
	s_add_u32 s10, s0, 0x16a4700
	s_addc_u32 s11, s1, 0
	s_add_u32 s12, s0, 0x16a4800
	s_addc_u32 s13, s1, 0
	s_add_u32 s14, s0, 0x16a4900
	s_addc_u32 s15, s1, 0
	s_add_u32 s16, s0, 0x16a4a00
	s_addc_u32 s17, s1, 0
	s_add_u32 s18, s0, 0x16a4b00
	s_addc_u32 s19, s1, 0
	s_add_u32 s20, s0, 0x16a4c00
	s_addc_u32 s21, s1, 0
	s_add_u32 s22, s0, 0x16a4d00
	s_addc_u32 s23, s1, 0
	s_add_u32 s24, s0, 0x16a4e00
	s_addc_u32 s25, s1, 0
	s_add_u32 s26, s0, 0x16a4f00
	s_addc_u32 s27, s1, 0
	s_add_u32 s28, s0, 0x16a5000
	s_addc_u32 s29, s1, 0
	s_add_u32 s30, s0, 0x16a5100
	s_addc_u32 s31, s1, 0
	s_add_u32 s34, s0, 0x16a5200
	s_addc_u32 s35, s1, 0
	s_add_u32 s36, s0, 0x16a5300
	s_addc_u32 s37, s1, 0
	s_add_u32 s38, s0, 0x16a5400
	s_addc_u32 s39, s1, 0
	s_mov_b32 s46, 1
	v_mov_b32_e32 v16, 0
	s_branch .LBB0_84

; DI unsigned xb_ld(unsigned* p) { return __hip_atomic_load(p, __ATOMIC_RELAXED, __HIP_MEMORY_SCOPE_AGENT); }
; DI void xcd_barrier_complete(unsigned* bar, unsigned x, unsigned& nloc, unsigned& nx) {
;     ...
;     for (unsigned j = 0; j < 16; ++j) { const unsigned c = xb_ld(&bar[XB_XCNT(j)]); sum += c; cnt += (c > 0u) ? 1u : 0u; mine = (j == x) ? c : mine; }
;     if (sum == G) break;
;     __builtin_amdgcn_s_sleep(1);
;     if ((++sp & 255u) == 0u) { if (xb_ld(&bar[XB_TMO])) break; if (sp > XB_SPIN_CAP) { atomicAdd(&bar[XB_TMO], 1u); break; } }
;   }
;   nloc = mine > 0u ? mine : 1u; nx = cnt > 0u ? cnt : 1u;
; }
; DI void xcd_barrier(const XcdBarrier& b) {
;   asm volatile("s_waitcnt vmcnt(0)" ::: "memory");
;   __syncthreads();
;   if (threadIdx.x == 0) {
;     unsigned* bar = b.bar;
;     __builtin_amdgcn_s_waitcnt(0);
;     unsigned nloc = b.st[0], nx = b.st[1];
;     if (nloc == 0u) { xcd_barrier_complete(bar, b.x, nloc, nx); b.st[0] = nloc; b.st[1] = nx; }
.LBB0_95:
	s_cmp_eq_u32 s33, 0
	s_cselect_b64 vcc, -1, 0
	s_cmp_eq_u32 s33, 1
	v_cndmask_b32_e32 v16, 0, v15, vcc
	s_cselect_b64 vcc, -1, 0
	s_cmp_eq_u32 s33, 2
	v_cndmask_b32_e32 v16, v16, v0, vcc
	s_cselect_b64 vcc, -1, 0
	s_cmp_eq_u32 s33, 3
	v_cndmask_b32_e32 v16, v16, v1, vcc
	s_cselect_b64 vcc, -1, 0
	s_cmp_eq_u32 s33, 4
	v_cndmask_b32_e32 v16, v16, v2, vcc
	s_cselect_b64 vcc, -1, 0
	s_cmp_eq_u32 s33, 5
	v_cndmask_b32_e32 v16, v16, v3, vcc
	s_cselect_b64 vcc, -1, 0
	s_cmp_eq_u32 s33, 6
	v_cndmask_b32_e32 v16, v16, v4, vcc
	s_cselect_b64 vcc, -1, 0
	s_cmp_eq_u32 s33, 7
	v_cndmask_b32_e32 v16, v16, v5, vcc
	s_cselect_b64 vcc, -1, 0
	s_cmp_eq_u32 s33, 8
	v_cndmask_b32_e32 v16, v16, v6, vcc
	s_cselect_b64 vcc, -1, 0
	s_cmp_eq_u32 s33, 9
	v_cndmask_b32_e32 v16, v16, v7, vcc
	s_cselect_b64 vcc, -1, 0
	s_cmp_eq_u32 s33, 10
	v_cndmask_b32_e32 v16, v16, v8, vcc
	s_cselect_b64 vcc, -1, 0
	s_cmp_eq_u32 s33, 11
	v_cndmask_b32_e32 v16, v16, v9, vcc
	s_cselect_b64 vcc, -1, 0
	s_cmp_eq_u32 s33, 12
	v_cndmask_b32_e32 v16, v16, v10, vcc
	s_cselect_b64 vcc, -1, 0
	s_cmp_eq_u32 s33, 13
	v_cndmask_b32_e32 v16, v16, v11, vcc
	s_cselect_b64 vcc, -1, 0
	s_cmp_eq_u32 s33, 14
	v_cndmask_b32_e32 v16, v16, v12, vcc
	s_cselect_b64 vcc, -1, 0
	s_cmp_eq_u32 s33, 15
	v_cndmask_b32_e32 v16, v16, v13, vcc
	s_cselect_b64 vcc, -1, 0
	v_cndmask_b32_e32 v16, v16, v14, vcc
	v_cmp_ne_u32_e32 vcc, 0, v15
	s_nop 1
	v_cndmask_b32_e64 v15, 0, 1, vcc
	v_cmp_ne_u32_e32 vcc, 0, v0
	s_nop 1
	v_addc_co_u32_e32 v0, vcc, 0, v15, vcc
	v_cmp_ne_u32_e32 vcc, 0, v1
	s_nop 1
	v_cndmask_b32_e64 v1, 0, 1, vcc
	v_cmp_ne_u32_e32 vcc, 0, v2
	v_max_u32_e32 v2, 1, v16
	s_nop 0
	v_addc_co_u32_e32 v0, vcc, v0, v1, vcc
	v_cmp_ne_u32_e32 vcc, 0, v3
	s_nop 1
	v_cndmask_b32_e64 v1, 0, 1, vcc
	v_cmp_ne_u32_e32 vcc, 0, v4
	s_nop 1
	v_addc_co_u32_e32 v0, vcc, v0, v1, vcc
	v_cmp_ne_u32_e32 vcc, 0, v5
	s_nop 1
	v_cndmask_b32_e64 v1, 0, 1, vcc
	v_cmp_ne_u32_e32 vcc, 0, v6
	s_nop 1
	v_addc_co_u32_e32 v0, vcc, v0, v1, vcc
	v_cmp_ne_u32_e32 vcc, 0, v7
	s_nop 1
	v_cndmask_b32_e64 v1, 0, 1, vcc
	v_cmp_ne_u32_e32 vcc, 0, v8
	s_nop 1
	v_addc_co_u32_e32 v0, vcc, v0, v1, vcc
	v_cmp_ne_u32_e32 vcc, 0, v9
	s_nop 1
	v_cndmask_b32_e64 v1, 0, 1, vcc
	v_cmp_ne_u32_e32 vcc, 0, v10
	s_nop 1
	v_addc_co_u32_e32 v0, vcc, v0, v1, vcc
	v_cmp_ne_u32_e32 vcc, 0, v11
	s_nop 1
	v_cndmask_b32_e64 v1, 0, 1, vcc
	v_cmp_ne_u32_e32 vcc, 0, v12
	s_nop 1
	v_addc_co_u32_e32 v0, vcc, v0, v1, vcc
	v_cmp_ne_u32_e32 vcc, 0, v13
	s_nop 1
	v_cndmask_b32_e64 v1, 0, 1, vcc
	v_cmp_ne_u32_e32 vcc, 0, v14
	s_nop 1
	v_addc_co_u32_e32 v0, vcc, v0, v1, vcc
	v_mov_b32_e32 v1, 0x20800
	v_max_u32_e32 v0, 1, v0
	v_mov_b32_e32 v252, v2
	v_mov_b32_e32 v1, 0x20804
	v_mov_b32_e32 v253, v0

; DI void xcd_barrier(const XcdBarrier& b) {
;   asm volatile("s_waitcnt vmcnt(0)" ::: "memory");
;   __syncthreads();
;   if (threadIdx.x == 0) {
;     unsigned* bar = b.bar;
;     __builtin_amdgcn_s_waitcnt(0);
;     unsigned nloc = b.st[0], nx = b.st[1];
;     if (nloc == 0u) { xcd_barrier_complete(bar, b.x, nloc, nx); b.st[0] = nloc; b.st[1] = nx; }
.LBB0_143:
	s_or_b64 exec, exec, s[14:15]
	s_mov_b32 s0, 0
	s_getreg_b32 s2, hwreg(HW_REG_XCC_ID, 0, 4)
	s_waitcnt vmcnt(0)
	s_waitcnt lgkmcnt(0)
	s_barrier
	s_mov_b64 s[4:5], exec
	v_readlane_b32 s6, v251, 5
	v_readlane_b32 s7, v251, 6
	s_and_b64 s[6:7], s[4:5], s[6:7]
	s_mov_b64 exec, s[6:7]
	s_cbranch_execz .LBB0_195
	s_ashr_i32 s1, s0, 31
	v_readlane_b32 s6, v251, 3
	v_readlane_b32 s7, v251, 4
	s_add_u32 s0, s6, s0
	s_addc_u32 s1, s7, s1
	v_mov_b32_e32 v0, 0x20800
	s_load_dwordx2 s[0:1], s[0:1], 0xf8
	s_waitcnt vmcnt(0) expcnt(0) lgkmcnt(0)
	v_mov_b32_e32 v2, v252
	v_mov_b32_e32 v0, 0x20804
	v_mov_b32_e32 v0, v253
	s_and_b32 s33, s2, 15
	s_waitcnt lgkmcnt(1)
	v_cmp_ne_u32_e32 vcc, 0, v2
	s_cbranch_vccnz .LBB0_159
	s_add_u32 s2, s0, 0x16a4300
	s_addc_u32 s3, s1, 0
	s_add_u32 s6, s0, 0x16a4500
	s_addc_u32 s7, s1, 0
	s_add_u32 s8, s0, 0x16a4600
	s_addc_u32 s9, s1, 0
	s_add_u32 s10, s0, 0x16a4700
	s_addc_u32 s11, s1, 0
	s_add_u32 s12, s0, 0x16a4800
	s_addc_u32 s13, s1, 0
	s_add_u32 s14, s0, 0x16a4900
	s_addc_u32 s15, s1, 0
	s_add_u32 s16, s0, 0x16a4a00
	s_addc_u32 s17, s1, 0
	s_add_u32 s18, s0, 0x16a4b00
	s_addc_u32 s19, s1, 0
	s_add_u32 s20, s0, 0x16a4c00
	s_addc_u32 s21, s1, 0
	s_add_u32 s22, s0, 0x16a4d00
	s_addc_u32 s23, s1, 0
	s_add_u32 s24, s0, 0x16a4e00
	s_addc_u32 s25, s1, 0
	s_add_u32 s26, s0, 0x16a4f00
	s_addc_u32 s27, s1, 0
	s_add_u32 s28, s0, 0x16a5000
	s_addc_u32 s29, s1, 0
	s_add_u32 s30, s0, 0x16a5100
	s_addc_u32 s31, s1, 0
	s_add_u32 s34, s0, 0x16a5200
	s_addc_u32 s35, s1, 0
	s_add_u32 s36, s0, 0x16a5300
	s_addc_u32 s37, s1, 0
	s_add_u32 s38, s0, 0x16a5400
	s_addc_u32 s39, s1, 0
	s_mov_b32 s46, 1
	v_mov_b32_e32 v16, 0
	s_branch .LBB0_147

; DI void xcd_barrier(const XcdBarrier& b) {
;   asm volatile("s_waitcnt vmcnt(0)" ::: "memory");
;   __syncthreads();
;   if (threadIdx.x == 0) {
;     unsigned* bar = b.bar;
;     __builtin_amdgcn_s_waitcnt(0);
;     unsigned nloc = b.st[0], nx = b.st[1];
;     if (nloc == 0u) { xcd_barrier_complete(bar, b.x, nloc, nx); b.st[0] = nloc; b.st[1] = nx; }
.LBB0_460:
	s_getreg_b32 s2, hwreg(HW_REG_XCC_ID, 0, 4)
	s_waitcnt vmcnt(0)
	s_barrier
	s_mov_b64 s[4:5], exec
	v_readlane_b32 s0, v251, 5
	v_readlane_b32 s1, v251, 6
	s_and_b64 s[0:1], s[4:5], s[0:1]
	s_mov_b64 exec, s[0:1]
	s_cbranch_execz .LBB0_512
	s_ashr_i32 s1, s33, 31
	v_readlane_b32 s6, v251, 3
	v_readlane_b32 s7, v251, 4
	s_add_u32 s0, s6, s33
	s_addc_u32 s1, s7, s1
	v_mov_b32_e32 v0, 0x20800
	s_load_dwordx2 s[0:1], s[0:1], 0xf8
	s_waitcnt vmcnt(0) expcnt(0) lgkmcnt(0)
	v_mov_b32_e32 v2, v252
	v_mov_b32_e32 v0, 0x20804
	v_mov_b32_e32 v0, v253
	s_and_b32 s33, s2, 15
	s_waitcnt lgkmcnt(1)
	v_cmp_ne_u32_e32 vcc, 0, v2
	s_cbranch_vccnz .LBB0_476
	s_add_u32 s2, s0, 0x16a4300
	s_addc_u32 s3, s1, 0
	s_add_u32 s6, s0, 0x16a4500
	s_addc_u32 s7, s1, 0
	s_add_u32 s8, s0, 0x16a4600
	s_addc_u32 s9, s1, 0
	s_add_u32 s10, s0, 0x16a4700
	s_addc_u32 s11, s1, 0
	s_add_u32 s12, s0, 0x16a4800
	s_addc_u32 s13, s1, 0
	s_add_u32 s14, s0, 0x16a4900
	s_addc_u32 s15, s1, 0
	s_add_u32 s16, s0, 0x16a4a00
	s_addc_u32 s17, s1, 0
	s_add_u32 s18, s0, 0x16a4b00
	s_addc_u32 s19, s1, 0
	s_add_u32 s20, s0, 0x16a4c00
	s_addc_u32 s21, s1, 0
	s_add_u32 s22, s0, 0x16a4d00
	s_addc_u32 s23, s1, 0
	s_add_u32 s24, s0, 0x16a4e00
	s_addc_u32 s25, s1, 0
	s_add_u32 s26, s0, 0x16a4f00
	s_addc_u32 s27, s1, 0
	s_add_u32 s28, s0, 0x16a5000
	s_addc_u32 s29, s1, 0
	s_add_u32 s30, s0, 0x16a5100
	s_addc_u32 s31, s1, 0
	s_add_u32 s34, s0, 0x16a5200
	s_addc_u32 s35, s1, 0
	s_add_u32 s36, s0, 0x16a5300
	s_addc_u32 s37, s1, 0
	s_add_u32 s38, s0, 0x16a5400
	s_addc_u32 s39, s1, 0
	s_mov_b32 s46, 1
	v_mov_b32_e32 v16, 0
	s_branch .LBB0_464

; #define VBID ((int)(blockIdx.x * 2 + (otid() >> 8)))
; #define LAS __attribute__((address_space(3)))
; template <class FA, class FB, class FL, class FS>
; DI void gemm_tile(char* lds, int ksteps, int rot, FA fa, FB fb, FL fl, FS fs) {
;   const int tid = VTID, lane = tid & 63, wave = tid >> 6;
;   const int wr = wave >> 1, wc = wave & 1, fr = lane & 15, fq = lane >> 4;
;   f32x4 acc[4][4];
; #pragma unroll
;   for (int m = 0; m < 4; ++m)
; #pragma unroll
;     for (int n = 0; n < 4; ++n) acc[m][n] = (f32x4){0.f, 0.f, 0.f, 0.f};
;   LAS char* l3 = (LAS char*)lds;
; #pragma unroll
;   for (int i = 0; i < 4; ++i) {
;     const int id = tid + i * 256, r = id >> 3, c = (id & 7) ^ (r & 7);
;     __builtin_amdgcn_global_load_lds((const unsigned*)fa(r, rot * 8 + c), (LAS unsigned*)(l3 + id * 16), 16, 0, 0);
;     __builtin_amdgcn_global_load_lds((const unsigned*)fb(r, rot * 8 + c), (LAS unsigned*)(l3 + 16384 + id * 16), 16, 0, 0);
;   }
;   asm volatile("s_waitcnt vmcnt(0)" ::: "memory");
;   __syncthreads();
; DI void phase_s5_e(const Params& p, char* lds) {
;     ...
;   for (int k_ = 0; k_ * VGRID < (nt); ++k_) {
;     int L = k_ * VGRID + VBID; const bool active_ = L < (nt); if (!active_) L = (nt) - 1;
;     const int g = L >> 4, mt = L & 15;
;     const bf16_t* Ag = ugm + (size_t)g * MP * 16 + (size_t)mt * 128 * 512;
;     gemm_tile(lds, 8, mt & 7,
;       [&](int r, int kc) { return Ag + (size_t)r * 512 + kc * 8; },
;       [&](int n, int kc) { return ME + (size_t)(g * 128 + n) * 512 + kc * 8; },
;       [&](int r, int c, f32x4 v) { *(f32x4*)(E + ((size_t)g * 2048 + mt * 128 + r) * 128 + c) = v; });
.LBB0_513:
	v_mov_b32_e32 v0, v182
	s_add_i32 s2, s2, s24
	v_mov_b32_e32 v31, v182
	v_ashrrev_i32_e32 v0, 8, v0
	v_add_u32_e32 v0, s2, v0
	v_lshrrev_b32_e32 v2, 4, v31
	v_and_b32_e32 v3, 0xff, v31
	v_and_b32_e32 v26, 15, v31
	v_and_b32_e32 v37, 7, v31
	v_bfe_u32 v25, v31, 6, 1
	v_bfe_u32 v33, v31, 3, 5
	v_bfe_u32 v27, v31, 7, 1
	v_lshl_add_u32 v36, v3, 4, v20
	v_or_b32_e32 v5, 0x100, v3
	v_or_b32_e32 v6, 0x200, v3
	v_or_b32_e32 v3, 0x300, v3
	v_bitop3_b32 v2, v2, v37, 3 bitop3:0x6c
	v_lshlrev_b32_e32 v7, 7, v26
	v_min_i32_e32 v0, 0x3ff, v0
	v_xor_b32_e32 v4, v33, v31
	v_lshrrev_b32_e32 v50, 3, v5
	v_lshrrev_b32_e32 v51, 3, v6
	v_lshrrev_b32_e32 v52, 3, v3
	v_lshl_add_u32 v45, v3, 4, v20
	v_lshl_or_b32 v116, v27, 13, v7
	v_lshl_or_b32 v117, v25, 13, v7
	v_lshl_add_u32 v3, v2, 4, v20
	v_ashrrev_i32_e32 v2, 4, v0
	v_lshlrev_b32_e32 v8, 3, v4
	v_lshl_add_u32 v42, v5, 4, v20
	v_lshl_add_u32 v44, v6, 4, v20
	v_and_b32_e32 v34, 7, v0
	v_xor_b32_e32 v4, v50, v31
	v_xor_b32_e32 v5, v51, v31
	v_xor_b32_e32 v6, v52, v31
	v_add_u32_e32 v30, v3, v116
	v_add_u32_e32 v32, v3, v117
	v_ashrrev_i32_e32 v3, 31, v2
	v_lshlrev_b32_e32 v9, 7, v2
	v_and_b32_e32 v29, 15, v0
	v_lshlrev_b32_e32 v7, 6, v34
	v_lshlrev_b32_e32 v10, 3, v4
	v_lshlrev_b32_e32 v11, 3, v5
	v_lshlrev_b32_e32 v12, 3, v6
	v_lshlrev_b64 v[4:5], 21, v[2:3]
	v_or_b32_e32 v6, v9, v33
	v_lshlrev_b32_e32 v0, 17, v29
	v_and_or_b32 v16, v8, 56, v7
	v_and_or_b32 v35, v10, 56, v7
	v_or_b32_e32 v8, v9, v50
	v_and_or_b32 v40, v11, 56, v7
	v_or_b32_e32 v10, v9, v51
	v_and_or_b32 v43, v12, 56, v7
	v_or_b32_e32 v12, v9, v52
	v_lshl_add_u64 v[4:5], s[4:5], 0, v[4:5]
	v_ashrrev_i32_e32 v7, 31, v6
	v_ashrrev_i32_e32 v9, 31, v8
	v_ashrrev_i32_e32 v11, 31, v10
	v_ashrrev_i32_e32 v13, 31, v12
	v_lshl_add_u64 v[18:19], v[4:5], 0, v[0:1]
	v_lshlrev_b32_e32 v0, 10, v33
	v_lshlrev_b64 v[4:5], 10, v[6:7]
	v_readfirstlane_b32 s2, v36
	v_add_u32_e32 v41, 0x4000, v36
	v_lshlrev_b64 v[6:7], 10, v[8:9]
	v_lshlrev_b64 v[8:9], 10, v[10:11]
	v_lshlrev_b64 v[14:15], 10, v[12:13]
	v_lshl_add_u64 v[10:11], v[18:19], 0, v[0:1]
	v_lshlrev_b32_e32 v0, 1, v16
	v_lshl_add_u64 v[12:13], s[6:7], 0, v[4:5]
	v_readfirstlane_b32 s20, v41
	v_lshl_add_u64 v[4:5], s[6:7], 0, v[14:15]
	v_lshl_add_u64 v[14:15], v[10:11], 0, v[0:1]
	v_lshl_add_u64 v[16:17], v[12:13], 0, v[0:1]
	v_lshlrev_b32_e32 v0, 10, v50
	s_mov_b32 m0, s2
	v_readfirstlane_b32 s19, v42
	v_add_u32_e32 v54, 0x4000, v42
	v_lshl_add_u64 v[6:7], s[6:7], 0, v[6:7]
	global_load_lds_dwordx4 v[14:15], off
	v_lshl_add_u64 v[14:15], v[18:19], 0, v[0:1]
	v_lshlrev_b32_e32 v0, 1, v35
	s_mov_b32 m0, s20
	v_readfirstlane_b32 s23, v54
	global_load_lds_dwordx4 v[16:17], off
	v_lshl_add_u64 v[16:17], v[14:15], 0, v[0:1]
	v_lshl_add_u64 v[38:39], v[6:7], 0, v[0:1]
	v_lshlrev_b32_e32 v0, 10, v51
	s_mov_b32 m0, s19
	v_readfirstlane_b32 s18, v44
	v_add_u32_e32 v53, 0x4000, v44
	v_lshl_add_u64 v[8:9], s[6:7], 0, v[8:9]
	global_load_lds_dwordx4 v[16:17], off
	v_lshl_add_u64 v[16:17], v[18:19], 0, v[0:1]
	v_lshlrev_b32_e32 v0, 1, v40
	s_mov_b32 m0, s23
	v_readfirstlane_b32 s22, v53
	global_load_lds_dwordx4 v[38:39], off
	v_lshl_add_u64 v[38:39], v[16:17], 0, v[0:1]
	v_lshl_add_u64 v[46:47], v[8:9], 0, v[0:1]
	v_lshlrev_b32_e32 v0, 10, v52
	s_mov_b32 m0, s18
	v_readfirstlane_b32 s17, v45
	v_add_u32_e32 v55, 0x4000, v45
	global_load_lds_dwordx4 v[38:39], off
	v_lshl_add_u64 v[18:19], v[18:19], 0, v[0:1]
	v_lshlrev_b32_e32 v0, 1, v43
	s_mov_b32 m0, s22
	v_readfirstlane_b32 s21, v55
	global_load_lds_dwordx4 v[46:47], off
	v_lshl_add_u64 v[38:39], v[18:19], 0, v[0:1]
	s_mov_b32 m0, s17
	v_lshl_add_u64 v[46:47], v[4:5], 0, v[0:1]
	global_load_lds_dwordx4 v[38:39], off
	s_mov_b32 m0, s21
	v_bfe_u32 v28, v31, 4, 2
	global_load_lds_dwordx4 v[46:47], off
	s_waitcnt vmcnt(0)
	s_waitcnt vmcnt(0) lgkmcnt(0)
	s_barrier
	ds_read_b128 v[56:59], v32 offset:16384
	ds_read_b128 v[60:63], v32 offset:18432
	ds_read_b128 v[46:49], v30
	ds_read_b128 v[64:67], v30 offset:2048
	ds_read_b128 v[72:75], v32 offset:20480
	ds_read_b128 v[80:83], v32 offset:22528
	v_bitop3_b32 v0, v28, v37, 4 bitop3:0x36
	ds_read_b128 v[104:107], v30 offset:4096
	ds_read_b128 v[108:111], v30 offset:6144
	v_lshl_add_u32 v0, v0, 4, v20
	v_bitop3_b32 v38, v52, 7, v31 bitop3:0x48
	v_lshlrev_b32_e32 v52, 3, v34
	v_bitop3_b32 v35, v33, 7, v31 bitop3:0x48
	v_bitop3_b32 v37, v50, 7, v31 bitop3:0x48
	v_bitop3_b32 v39, v51, 7, v31 bitop3:0x48
	v_add_u32_e32 v31, v0, v116
	v_add_u32_e32 v33, v0, v117
	v_add_u32_e32 v0, 8, v52
	v_cmp_ne_u32_e32 vcc, 7, v34
	s_waitcnt lgkmcnt(5)
	v_mfma_f32_16x16x32_bf16 v[68:71], v[56:59], v[46:49], 0
	v_add_u32_e32 v40, 0x8000, v36
	v_cndmask_b32_e32 v0, 0, v0, vcc
	v_or_b32_e32 v124, v0, v35
	v_mfma_f32_16x16x32_bf16 v[76:79], v[60:63], v[46:49], 0
	v_or_b32_e32 v146, v0, v37
	v_or_b32_e32 v147, v0, v39
	v_or_b32_e32 v158, v0, v38
	s_waitcnt lgkmcnt(3)
	v_mfma_f32_16x16x32_bf16 v[84:87], v[72:75], v[46:49], 0
	v_lshlrev_b32_e32 v0, 4, v124
	ds_read_b128 v[124:127], v33 offset:16384
	ds_read_b128 v[128:131], v33 offset:18432
	v_add_u32_e32 v43, 0xc000, v36
	s_waitcnt lgkmcnt(4)
	v_mfma_f32_16x16x32_bf16 v[88:91], v[80:83], v[46:49], 0
	v_readfirstlane_b32 s10, v40
	v_readfirstlane_b32 s3, v43
	v_add_u32_e32 v46, 0x8000, v42
	v_mfma_f32_16x16x32_bf16 v[92:95], v[56:59], v[64:67], 0
	v_lshl_add_u64 v[144:145], v[10:11], 0, v[0:1]
	s_mov_b32 m0, s10
	v_add_u32_e32 v47, 0xc000, v42
	v_mfma_f32_16x16x32_bf16 v[96:99], v[60:63], v[64:67], 0
	v_readfirstlane_b32 s16, v46
	v_lshl_add_u64 v[148:149], v[12:13], 0, v[0:1]
	v_lshlrev_b32_e32 v0, 4, v146
	v_mfma_f32_16x16x32_bf16 v[100:103], v[72:75], v[64:67], 0
	v_add_u32_e32 v50, 0x8000, v44
	v_readfirstlane_b32 s15, v47
	v_lshl_add_u64 v[150:151], v[14:15], 0, v[0:1]
	v_mfma_f32_16x16x32_bf16 v[64:67], v[80:83], v[64:67], 0
	v_lshl_add_u64 v[152:153], v[6:7], 0, v[0:1]
	v_lshlrev_b32_e32 v0, 4, v147
	v_add_u32_e32 v48, 0xc000, v44
	s_waitcnt lgkmcnt(3)
; #define MFMA16(a, b, c) __builtin_amdgcn_mfma_f32_16x16x32_bf16((a), (b), (c), 0, 0, 0)
; #define LAS __attribute__((address_space(3)))
; template <class FA, class FB, class FL, class FS>
; DI void gemm_tile(char* lds, int ksteps, int rot, FA fa, FB fb, FL fl, FS fs) {
;     ...
;   for (int ks = 0; ks < ksteps; ++ks) {
;     const int cur = ks & 1;
;     if (ks + 1 < ksteps) {
;       int kn = ks + 1 + rot; if (kn >= ksteps) kn -= ksteps;
;       LAS char* dst = l3 + (cur ^ 1) * 32768;
; #pragma unroll
;       for (int i = 0; i < 4; ++i) {
;         const int id = tid + i * 256, r = id >> 3, c = (id & 7) ^ (r & 7);
;         __builtin_amdgcn_global_load_lds((const unsigned*)fa(r, kn * 8 + c), (LAS unsigned*)(dst + id * 16), 16, 0, 0);
;         __builtin_amdgcn_global_load_lds((const unsigned*)fb(r, kn * 8 + c), (LAS unsigned*)(dst + 16384 + id * 16), 16, 0, 0);
;       }
;     }
;     const char* A = lds + cur * 32768;
;     const char* B = A + 16384;
; #pragma unroll
;     for (int kk = 0; kk < 2; ++kk) {
;       bf16x8 af[4], bq[4];
; #pragma unroll
;       for (int m = 0; m < 4; ++m) af[m] = ldfrag(A, 128, wr * 64 + m * 16 + fr, kk * 4 + fq);
; #pragma unroll
;       for (int n = 0; n < 4; ++n) bq[n] = ldfrag(B, 128, wc * 64 + n * 16 + fr, kk * 4 + fq);
; #pragma unroll
;       for (int m = 0; m < 4; ++m)
; #pragma unroll
;         for (int n = 0; n < 4; ++n) acc[m][n] = MFMA16(bq[n], af[m], acc[m][n]);
;     }
;     asm volatile("s_waitcnt vmcnt(0)" ::: "memory");
;     __syncthreads();
	v_mfma_f32_16x16x32_bf16 v[112:115], v[56:59], v[104:107], 0
	v_readfirstlane_b32 s14, v50
	v_add_u32_e32 v49, 0x8000, v45
	v_readfirstlane_b32 s13, v48
	v_mfma_f32_16x16x32_bf16 v[116:119], v[60:63], v[104:107], 0
	v_lshl_add_u64 v[154:155], v[16:17], 0, v[0:1]
	v_add_u32_e32 v51, 0xc000, v45
	v_readfirstlane_b32 s12, v49
	v_mfma_f32_16x16x32_bf16 v[120:123], v[72:75], v[104:107], 0
	v_lshl_add_u64 v[156:157], v[8:9], 0, v[0:1]
	v_lshlrev_b32_e32 v0, 4, v158
	v_readfirstlane_b32 s11, v51
	v_mfma_f32_16x16x32_bf16 v[104:107], v[80:83], v[104:107], 0
	v_lshl_add_u64 v[158:159], v[4:5], 0, v[0:1]
	v_cmp_lt_u32_e32 vcc, 5, v34
	v_lshlrev_b64 v[2:3], 11, v[2:3]
	s_waitcnt lgkmcnt(2)
	v_mfma_f32_16x16x32_bf16 v[56:59], v[56:59], v[108:111], 0
	s_add_i32 s1, s1, 1
	s_add_i32 s0, s0, s25
	s_cmpk_lt_i32 s0, 0x400
	v_mfma_f32_16x16x32_bf16 v[60:63], v[60:63], v[108:111], 0
	v_mfma_f32_16x16x32_bf16 v[72:75], v[72:75], v[108:111], 0
	v_mfma_f32_16x16x32_bf16 v[80:83], v[80:83], v[108:111], 0
	ds_read_b128 v[108:111], v31
	ds_read_b128 v[132:135], v31 offset:2048
	ds_read_b128 v[136:139], v33 offset:20480
	ds_read_b128 v[140:143], v33 offset:22528
	global_load_lds_dwordx4 v[144:145], off
	s_mov_b32 m0, s3
	s_waitcnt lgkmcnt(0)
	v_mfma_f32_16x16x32_bf16 v[68:71], v[124:127], v[108:111], v[68:71]
	v_mfma_f32_16x16x32_bf16 v[76:79], v[128:131], v[108:111], v[76:79]
	v_mfma_f32_16x16x32_bf16 v[84:87], v[136:139], v[108:111], v[84:87]
	v_mfma_f32_16x16x32_bf16 v[88:91], v[140:143], v[108:111], v[88:91]
	ds_read_b128 v[108:111], v31 offset:4096
	ds_read_b128 v[144:147], v31 offset:6144
	global_load_lds_dwordx4 v[148:149], off
	s_mov_b32 m0, s16
	v_lshl_add_u64 v[148:149], v[18:19], 0, v[0:1]
	global_load_lds_dwordx4 v[150:151], off
	s_mov_b32 m0, s15
	v_mfma_f32_16x16x32_bf16 v[92:95], v[124:127], v[132:135], v[92:95]
	global_load_lds_dwordx4 v[152:153], off
	s_mov_b32 m0, s14
	v_mfma_f32_16x16x32_bf16 v[96:99], v[128:131], v[132:135], v[96:99]
	global_load_lds_dwordx4 v[154:155], off
	s_mov_b32 m0, s13
	v_mfma_f32_16x16x32_bf16 v[100:103], v[136:139], v[132:135], v[100:103]
	global_load_lds_dwordx4 v[156:157], off
	s_mov_b32 m0, s12
	v_mfma_f32_16x16x32_bf16 v[64:67], v[140:143], v[132:135], v[64:67]
	global_load_lds_dwordx4 v[148:149], off
	s_mov_b32 m0, s11
	s_waitcnt lgkmcnt(0)
	v_mfma_f32_16x16x32_bf16 v[112:115], v[124:127], v[108:111], v[112:115]
	global_load_lds_dwordx4 v[158:159], off
	s_waitcnt vmcnt(0)
	v_mfma_f32_16x16x32_bf16 v[116:119], v[128:131], v[108:111], v[116:119]
	s_waitcnt vmcnt(0) lgkmcnt(0)
	s_barrier
	v_mfma_f32_16x16x32_bf16 v[120:123], v[136:139], v[108:111], v[120:123]
	v_cndmask_b32_e32 v0, 16, v21, vcc
	v_add_u32_e32 v0, v0, v52
	s_mov_b32 m0, s2
	v_mfma_f32_16x16x32_bf16 v[104:107], v[140:143], v[108:111], v[104:107]
	v_cmp_lt_u32_e32 vcc, 4, v34
	v_mfma_f32_16x16x32_bf16 v[56:59], v[124:127], v[144:147], v[56:59]
	ds_read_b128 v[108:111], v32 offset:49152
	ds_read_b128 v[124:127], v32 offset:51200
	v_mfma_f32_16x16x32_bf16 v[60:63], v[128:131], v[144:147], v[60:63]
	ds_read_b128 v[128:131], v30 offset:32768
	ds_read_b128 v[132:135], v30 offset:34816
	v_mfma_f32_16x16x32_bf16 v[72:75], v[136:139], v[144:147], v[72:75]
	ds_read_b128 v[136:139], v32 offset:53248
	v_mfma_f32_16x16x32_bf16 v[80:83], v[140:143], v[144:147], v[80:83]
	ds_read_b128 v[140:143], v32 offset:55296
	v_or_b32_e32 v147, v0, v39
	v_or_b32_e32 v144, v0, v35
	s_waitcnt lgkmcnt(3)
	v_mfma_f32_16x16x32_bf16 v[68:71], v[108:111], v[128:131], v[68:71]
	v_or_b32_e32 v145, v0, v37
	v_lshlrev_b32_e32 v144, 3, v144
	v_lshlrev_b32_e32 v146, 3, v145
	v_mfma_f32_16x16x32_bf16 v[76:79], v[124:127], v[128:131], v[76:79]
	v_ashrrev_i32_e32 v145, 31, v144
	v_lshlrev_b64 v[144:145], 1, v[144:145]
	v_lshl_add_u64 v[152:153], v[10:11], 0, v[144:145]
	s_waitcnt lgkmcnt(1)
	v_mfma_f32_16x16x32_bf16 v[84:87], v[136:139], v[128:131], v[84:87]
	v_lshl_add_u64 v[154:155], v[12:13], 0, v[144:145]
	v_or_b32_e32 v0, v0, v38
	v_lshlrev_b32_e32 v148, 3, v0
	s_waitcnt lgkmcnt(0)
	v_mfma_f32_16x16x32_bf16 v[88:91], v[140:143], v[128:131], v[88:91]
	v_ashrrev_i32_e32 v149, 31, v148
	v_lshlrev_b64 v[148:149], 1, v[148:149]
	v_lshl_add_u64 v[160:161], v[4:5], 0, v[148:149]
	v_mfma_f32_16x16x32_bf16 v[92:95], v[108:111], v[132:135], v[92:95]
	v_lshl_add_u64 v[148:149], v[18:19], 0, v[148:149]
	v_cndmask_b32_e32 v0, 24, v22, vcc
	v_add_u32_e32 v0, v0, v52
	v_mfma_f32_16x16x32_bf16 v[96:99], v[124:127], v[132:135], v[96:99]
	v_cmp_lt_u32_e32 vcc, 3, v34
	v_mfma_f32_16x16x32_bf16 v[100:103], v[136:139], v[132:135], v[100:103]
	v_mfma_f32_16x16x32_bf16 v[64:67], v[140:143], v[132:135], v[64:67]
	ds_read_b128 v[128:131], v30 offset:36864
	ds_read_b128 v[132:135], v30 offset:38912
	s_waitcnt lgkmcnt(1)
	v_mfma_f32_16x16x32_bf16 v[112:115], v[108:111], v[128:131], v[112:115]
	v_mfma_f32_16x16x32_bf16 v[116:119], v[124:127], v[128:131], v[116:119]
	v_mfma_f32_16x16x32_bf16 v[120:123], v[136:139], v[128:131], v[120:123]
	v_mfma_f32_16x16x32_bf16 v[104:107], v[140:143], v[128:131], v[104:107]
	v_lshlrev_b32_e32 v128, 3, v147
	v_ashrrev_i32_e32 v129, 31, v128
	v_lshlrev_b64 v[150:151], 1, v[128:129]
	s_waitcnt lgkmcnt(0)
	v_mfma_f32_16x16x32_bf16 v[56:59], v[108:111], v[132:135], v[56:59]
	v_ashrrev_i32_e32 v147, 31, v146
	v_lshlrev_b64 v[146:147], 1, v[146:147]
	v_lshl_add_u64 v[156:157], v[6:7], 0, v[146:147]
	v_mfma_f32_16x16x32_bf16 v[60:63], v[124:127], v[132:135], v[60:63]
	ds_read_b128 v[108:111], v33 offset:49152
	ds_read_b128 v[124:127], v33 offset:51200
	v_lshl_add_u64 v[162:163], v[14:15], 0, v[146:147]
	v_lshl_add_u64 v[158:159], v[8:9], 0, v[150:151]
	v_mfma_f32_16x16x32_bf16 v[72:75], v[136:139], v[132:135], v[72:75]
	v_lshl_add_u64 v[150:151], v[16:17], 0, v[150:151]
	v_mfma_f32_16x16x32_bf16 v[80:83], v[140:143], v[132:135], v[80:83]
	ds_read_b128 v[128:131], v31 offset:32768
	ds_read_b128 v[132:135], v31 offset:34816
	ds_read_b128 v[136:139], v33 offset:53248
	ds_read_b128 v[140:143], v33 offset:55296
	global_load_lds_dwordx4 v[152:153], off
	s_mov_b32 m0, s20
	s_waitcnt lgkmcnt(0)
; #define MFMA16(a, b, c) __builtin_amdgcn_mfma_f32_16x16x32_bf16((a), (b), (c), 0, 0, 0)
; #define LAS __attribute__((address_space(3)))
; template <class FA, class FB, class FL, class FS>
; DI void gemm_tile(char* lds, int ksteps, int rot, FA fa, FB fb, FL fl, FS fs) {
;     ...
;   for (int ks = 0; ks < ksteps; ++ks) {
;     const int cur = ks & 1;
;     if (ks + 1 < ksteps) {
;       int kn = ks + 1 + rot; if (kn >= ksteps) kn -= ksteps;
;       LAS char* dst = l3 + (cur ^ 1) * 32768;
; #pragma unroll
;       for (int i = 0; i < 4; ++i) {
;         const int id = tid + i * 256, r = id >> 3, c = (id & 7) ^ (r & 7);
;         __builtin_amdgcn_global_load_lds((const unsigned*)fa(r, kn * 8 + c), (LAS unsigned*)(dst + id * 16), 16, 0, 0);
;         __builtin_amdgcn_global_load_lds((const unsigned*)fb(r, kn * 8 + c), (LAS unsigned*)(dst + 16384 + id * 16), 16, 0, 0);
;       }
;     }
;     const char* A = lds + cur * 32768;
;     const char* B = A + 16384;
; #pragma unroll
;     for (int kk = 0; kk < 2; ++kk) {
;       bf16x8 af[4], bq[4];
; #pragma unroll
;       for (int m = 0; m < 4; ++m) af[m] = ldfrag(A, 128, wr * 64 + m * 16 + fr, kk * 4 + fq);
; #pragma unroll
;       for (int n = 0; n < 4; ++n) bq[n] = ldfrag(B, 128, wc * 64 + n * 16 + fr, kk * 4 + fq);
; #pragma unroll
;       for (int m = 0; m < 4; ++m)
; #pragma unroll
;         for (int n = 0; n < 4; ++n) acc[m][n] = MFMA16(bq[n], af[m], acc[m][n]);
;     }
;     asm volatile("s_waitcnt vmcnt(0)" ::: "memory");
;     __syncthreads();
	v_mfma_f32_16x16x32_bf16 v[68:71], v[108:111], v[128:131], v[68:71]
	v_mfma_f32_16x16x32_bf16 v[76:79], v[124:127], v[128:131], v[76:79]
	v_mfma_f32_16x16x32_bf16 v[84:87], v[136:139], v[128:131], v[84:87]
	v_mfma_f32_16x16x32_bf16 v[88:91], v[140:143], v[128:131], v[88:91]
	ds_read_b128 v[128:131], v31 offset:36864
	ds_read_b128 v[144:147], v31 offset:38912
	global_load_lds_dwordx4 v[154:155], off
	s_mov_b32 m0, s19
	v_mfma_f32_16x16x32_bf16 v[92:95], v[108:111], v[132:135], v[92:95]
	global_load_lds_dwordx4 v[162:163], off
	s_mov_b32 m0, s23
	v_mfma_f32_16x16x32_bf16 v[96:99], v[124:127], v[132:135], v[96:99]
	global_load_lds_dwordx4 v[156:157], off
	s_mov_b32 m0, s18
	v_mfma_f32_16x16x32_bf16 v[100:103], v[136:139], v[132:135], v[100:103]
	global_load_lds_dwordx4 v[150:151], off
	s_mov_b32 m0, s22
	v_mfma_f32_16x16x32_bf16 v[64:67], v[140:143], v[132:135], v[64:67]
	global_load_lds_dwordx4 v[158:159], off
	s_mov_b32 m0, s17
	s_waitcnt lgkmcnt(0)
	v_mfma_f32_16x16x32_bf16 v[112:115], v[108:111], v[128:131], v[112:115]
	global_load_lds_dwordx4 v[148:149], off
	s_mov_b32 m0, s21
	v_mfma_f32_16x16x32_bf16 v[116:119], v[124:127], v[128:131], v[116:119]
	global_load_lds_dwordx4 v[160:161], off
	s_waitcnt vmcnt(0)
	v_mfma_f32_16x16x32_bf16 v[120:123], v[136:139], v[128:131], v[120:123]
	s_waitcnt vmcnt(0) lgkmcnt(0)
	s_barrier
	v_mfma_f32_16x16x32_bf16 v[104:107], v[140:143], v[128:131], v[104:107]
	s_mov_b32 m0, s10
	v_mfma_f32_16x16x32_bf16 v[56:59], v[108:111], v[144:147], v[56:59]
	v_mfma_f32_16x16x32_bf16 v[60:63], v[124:127], v[144:147], v[60:63]
	ds_read_b128 v[108:111], v32 offset:16384
	ds_read_b128 v[124:127], v32 offset:18432
	ds_read_b128 v[128:131], v30
	ds_read_b128 v[132:135], v30 offset:2048
	v_mfma_f32_16x16x32_bf16 v[72:75], v[136:139], v[144:147], v[72:75]
	ds_read_b128 v[136:139], v32 offset:20480
	v_mfma_f32_16x16x32_bf16 v[80:83], v[140:143], v[144:147], v[80:83]
	ds_read_b128 v[140:143], v32 offset:22528
	v_or_b32_e32 v147, v0, v39
	v_or_b32_e32 v144, v0, v35
	s_waitcnt lgkmcnt(3)
	v_mfma_f32_16x16x32_bf16 v[68:71], v[108:111], v[128:131], v[68:71]
	v_or_b32_e32 v145, v0, v37
	v_lshlrev_b32_e32 v144, 3, v144
	v_lshlrev_b32_e32 v146, 3, v145
	v_mfma_f32_16x16x32_bf16 v[76:79], v[124:127], v[128:131], v[76:79]
	v_ashrrev_i32_e32 v145, 31, v144
	v_lshlrev_b64 v[144:145], 1, v[144:145]
	v_lshl_add_u64 v[152:153], v[10:11], 0, v[144:145]
	s_waitcnt lgkmcnt(1)
	v_mfma_f32_16x16x32_bf16 v[84:87], v[136:139], v[128:131], v[84:87]
	v_lshl_add_u64 v[154:155], v[12:13], 0, v[144:145]
	v_or_b32_e32 v0, v0, v38
	v_lshlrev_b32_e32 v148, 3, v0
	s_waitcnt lgkmcnt(0)
	v_mfma_f32_16x16x32_bf16 v[88:91], v[140:143], v[128:131], v[88:91]
	v_ashrrev_i32_e32 v149, 31, v148
	v_lshlrev_b64 v[148:149], 1, v[148:149]
	v_lshl_add_u64 v[160:161], v[4:5], 0, v[148:149]
	v_mfma_f32_16x16x32_bf16 v[92:95], v[108:111], v[132:135], v[92:95]
	v_lshl_add_u64 v[148:149], v[18:19], 0, v[148:149]
	v_cndmask_b32_e32 v0, 32, v23, vcc
	v_add_u32_e32 v0, v0, v52
	v_mfma_f32_16x16x32_bf16 v[96:99], v[124:127], v[132:135], v[96:99]
	v_cmp_lt_u32_e32 vcc, 2, v34
	v_mfma_f32_16x16x32_bf16 v[100:103], v[136:139], v[132:135], v[100:103]
	v_mfma_f32_16x16x32_bf16 v[64:67], v[140:143], v[132:135], v[64:67]
	ds_read_b128 v[128:131], v30 offset:4096
	ds_read_b128 v[132:135], v30 offset:6144
	s_waitcnt lgkmcnt(1)
	v_mfma_f32_16x16x32_bf16 v[112:115], v[108:111], v[128:131], v[112:115]
	v_mfma_f32_16x16x32_bf16 v[116:119], v[124:127], v[128:131], v[116:119]
	v_mfma_f32_16x16x32_bf16 v[120:123], v[136:139], v[128:131], v[120:123]
	v_mfma_f32_16x16x32_bf16 v[104:107], v[140:143], v[128:131], v[104:107]
	v_lshlrev_b32_e32 v128, 3, v147
	v_ashrrev_i32_e32 v129, 31, v128
	v_lshlrev_b64 v[150:151], 1, v[128:129]
	s_waitcnt lgkmcnt(0)
	v_mfma_f32_16x16x32_bf16 v[56:59], v[108:111], v[132:135], v[56:59]
	v_ashrrev_i32_e32 v147, 31, v146
	v_lshlrev_b64 v[146:147], 1, v[146:147]
	v_lshl_add_u64 v[156:157], v[6:7], 0, v[146:147]
	v_mfma_f32_16x16x32_bf16 v[60:63], v[124:127], v[132:135], v[60:63]
	ds_read_b128 v[108:111], v33 offset:16384
	ds_read_b128 v[124:127], v33 offset:18432
	v_lshl_add_u64 v[162:163], v[14:15], 0, v[146:147]
	v_lshl_add_u64 v[158:159], v[8:9], 0, v[150:151]
	v_mfma_f32_16x16x32_bf16 v[72:75], v[136:139], v[132:135], v[72:75]
	v_lshl_add_u64 v[150:151], v[16:17], 0, v[150:151]
	v_mfma_f32_16x16x32_bf16 v[80:83], v[140:143], v[132:135], v[80:83]
	ds_read_b128 v[128:131], v31
	ds_read_b128 v[132:135], v31 offset:2048
	ds_read_b128 v[136:139], v33 offset:20480
	ds_read_b128 v[140:143], v33 offset:22528
	global_load_lds_dwordx4 v[152:153], off
	s_mov_b32 m0, s3
	s_waitcnt lgkmcnt(0)
	v_mfma_f32_16x16x32_bf16 v[68:71], v[108:111], v[128:131], v[68:71]
	v_mfma_f32_16x16x32_bf16 v[76:79], v[124:127], v[128:131], v[76:79]
	v_mfma_f32_16x16x32_bf16 v[84:87], v[136:139], v[128:131], v[84:87]
	v_mfma_f32_16x16x32_bf16 v[88:91], v[140:143], v[128:131], v[88:91]
	ds_read_b128 v[128:131], v31 offset:4096
	ds_read_b128 v[144:147], v31 offset:6144
	global_load_lds_dwordx4 v[154:155], off
	s_mov_b32 m0, s16
	v_mfma_f32_16x16x32_bf16 v[92:95], v[108:111], v[132:135], v[92:95]
	global_load_lds_dwordx4 v[162:163], off
	s_mov_b32 m0, s15
	v_mfma_f32_16x16x32_bf16 v[96:99], v[124:127], v[132:135], v[96:99]
	global_load_lds_dwordx4 v[156:157], off
	s_mov_b32 m0, s14
	v_mfma_f32_16x16x32_bf16 v[100:103], v[136:139], v[132:135], v[100:103]
	global_load_lds_dwordx4 v[150:151], off
	s_mov_b32 m0, s13
	v_mfma_f32_16x16x32_bf16 v[64:67], v[140:143], v[132:135], v[64:67]
	global_load_lds_dwordx4 v[158:159], off
	s_mov_b32 m0, s12
	s_waitcnt lgkmcnt(0)
	v_mfma_f32_16x16x32_bf16 v[112:115], v[108:111], v[128:131], v[112:115]
	global_load_lds_dwordx4 v[148:149], off
	s_mov_b32 m0, s11
	v_mfma_f32_16x16x32_bf16 v[116:119], v[124:127], v[128:131], v[116:119]
	global_load_lds_dwordx4 v[160:161], off
	s_waitcnt vmcnt(0)
	v_mfma_f32_16x16x32_bf16 v[120:123], v[136:139], v[128:131], v[120:123]
	s_waitcnt vmcnt(0) lgkmcnt(0)
	s_barrier
; #define MFMA16(a, b, c) __builtin_amdgcn_mfma_f32_16x16x32_bf16((a), (b), (c), 0, 0, 0)
; #define LAS __attribute__((address_space(3)))
; template <class FA, class FB, class FL, class FS>
; DI void gemm_tile(char* lds, int ksteps, int rot, FA fa, FB fb, FL fl, FS fs) {
;     ...
;   for (int ks = 0; ks < ksteps; ++ks) {
;     const int cur = ks & 1;
;     if (ks + 1 < ksteps) {
;       int kn = ks + 1 + rot; if (kn >= ksteps) kn -= ksteps;
;       LAS char* dst = l3 + (cur ^ 1) * 32768;
; #pragma unroll
;       for (int i = 0; i < 4; ++i) {
;         const int id = tid + i * 256, r = id >> 3, c = (id & 7) ^ (r & 7);
;         __builtin_amdgcn_global_load_lds((const unsigned*)fa(r, kn * 8 + c), (LAS unsigned*)(dst + id * 16), 16, 0, 0);
;         __builtin_amdgcn_global_load_lds((const unsigned*)fb(r, kn * 8 + c), (LAS unsigned*)(dst + 16384 + id * 16), 16, 0, 0);
;       }
;     }
;     const char* A = lds + cur * 32768;
;     const char* B = A + 16384;
; #pragma unroll
;     for (int kk = 0; kk < 2; ++kk) {
;       bf16x8 af[4], bq[4];
; #pragma unroll
;       for (int m = 0; m < 4; ++m) af[m] = ldfrag(A, 128, wr * 64 + m * 16 + fr, kk * 4 + fq);
; #pragma unroll
;       for (int n = 0; n < 4; ++n) bq[n] = ldfrag(B, 128, wc * 64 + n * 16 + fr, kk * 4 + fq);
; #pragma unroll
;       for (int m = 0; m < 4; ++m)
; #pragma unroll
;         for (int n = 0; n < 4; ++n) acc[m][n] = MFMA16(bq[n], af[m], acc[m][n]);
;     }
;     asm volatile("s_waitcnt vmcnt(0)" ::: "memory");
;     __syncthreads();
	v_mfma_f32_16x16x32_bf16 v[104:107], v[140:143], v[128:131], v[104:107]
	s_mov_b32 m0, s2
	v_readfirstlane_b32 s2, v36
	v_mfma_f32_16x16x32_bf16 v[56:59], v[108:111], v[144:147], v[56:59]
	v_mfma_f32_16x16x32_bf16 v[60:63], v[124:127], v[144:147], v[60:63]
	ds_read_b128 v[108:111], v32 offset:49152
	ds_read_b128 v[124:127], v32 offset:51200
	ds_read_b128 v[128:131], v30 offset:32768
	ds_read_b128 v[132:135], v30 offset:34816
	v_mfma_f32_16x16x32_bf16 v[72:75], v[136:139], v[144:147], v[72:75]
	ds_read_b128 v[136:139], v32 offset:53248
	v_mfma_f32_16x16x32_bf16 v[80:83], v[140:143], v[144:147], v[80:83]
	ds_read_b128 v[140:143], v32 offset:55296
	v_or_b32_e32 v147, v0, v39
	v_or_b32_e32 v144, v0, v35
	s_waitcnt lgkmcnt(3)
	v_mfma_f32_16x16x32_bf16 v[68:71], v[108:111], v[128:131], v[68:71]
	v_or_b32_e32 v145, v0, v37
	v_lshlrev_b32_e32 v144, 3, v144
	v_lshlrev_b32_e32 v146, 3, v145
	v_mfma_f32_16x16x32_bf16 v[76:79], v[124:127], v[128:131], v[76:79]
	v_ashrrev_i32_e32 v145, 31, v144
	v_lshlrev_b64 v[144:145], 1, v[144:145]
	v_lshl_add_u64 v[152:153], v[10:11], 0, v[144:145]
	s_waitcnt lgkmcnt(1)
	v_mfma_f32_16x16x32_bf16 v[84:87], v[136:139], v[128:131], v[84:87]
	v_lshl_add_u64 v[154:155], v[12:13], 0, v[144:145]
	v_or_b32_e32 v0, v0, v38
	v_lshlrev_b32_e32 v148, 3, v0
	s_waitcnt lgkmcnt(0)
	v_mfma_f32_16x16x32_bf16 v[88:91], v[140:143], v[128:131], v[88:91]
	v_ashrrev_i32_e32 v149, 31, v148
	v_lshlrev_b64 v[148:149], 1, v[148:149]
	v_lshl_add_u64 v[160:161], v[4:5], 0, v[148:149]
	v_mfma_f32_16x16x32_bf16 v[92:95], v[108:111], v[132:135], v[92:95]
	v_lshl_add_u64 v[148:149], v[18:19], 0, v[148:149]
	v_cndmask_b32_e32 v0, 40, v24, vcc
	v_add_u32_e32 v0, v0, v52
	v_mfma_f32_16x16x32_bf16 v[96:99], v[124:127], v[132:135], v[96:99]
	v_cmp_lt_u32_e32 vcc, 1, v34
	v_mfma_f32_16x16x32_bf16 v[100:103], v[136:139], v[132:135], v[100:103]
	v_mfma_f32_16x16x32_bf16 v[64:67], v[140:143], v[132:135], v[64:67]
	ds_read_b128 v[128:131], v30 offset:36864
	ds_read_b128 v[132:135], v30 offset:38912
	s_waitcnt lgkmcnt(1)
	v_mfma_f32_16x16x32_bf16 v[112:115], v[108:111], v[128:131], v[112:115]
	v_mfma_f32_16x16x32_bf16 v[116:119], v[124:127], v[128:131], v[116:119]
	v_mfma_f32_16x16x32_bf16 v[120:123], v[136:139], v[128:131], v[120:123]
	v_mfma_f32_16x16x32_bf16 v[104:107], v[140:143], v[128:131], v[104:107]
	v_lshlrev_b32_e32 v128, 3, v147
	v_ashrrev_i32_e32 v129, 31, v128
	v_lshlrev_b64 v[150:151], 1, v[128:129]
	s_waitcnt lgkmcnt(0)
	v_mfma_f32_16x16x32_bf16 v[56:59], v[108:111], v[132:135], v[56:59]
	v_ashrrev_i32_e32 v147, 31, v146
	v_lshlrev_b64 v[146:147], 1, v[146:147]
	v_lshl_add_u64 v[156:157], v[6:7], 0, v[146:147]
	v_mfma_f32_16x16x32_bf16 v[60:63], v[124:127], v[132:135], v[60:63]
	ds_read_b128 v[108:111], v33 offset:49152
	ds_read_b128 v[124:127], v33 offset:51200
	v_lshl_add_u64 v[162:163], v[14:15], 0, v[146:147]
	v_lshl_add_u64 v[158:159], v[8:9], 0, v[150:151]
	v_mfma_f32_16x16x32_bf16 v[72:75], v[136:139], v[132:135], v[72:75]
	v_lshl_add_u64 v[150:151], v[16:17], 0, v[150:151]
	v_mfma_f32_16x16x32_bf16 v[80:83], v[140:143], v[132:135], v[80:83]
	ds_read_b128 v[128:131], v31 offset:32768
	ds_read_b128 v[132:135], v31 offset:34816
	ds_read_b128 v[136:139], v33 offset:53248
	ds_read_b128 v[140:143], v33 offset:55296
	global_load_lds_dwordx4 v[152:153], off
	s_mov_b32 m0, s20
	s_waitcnt lgkmcnt(0)
	v_mfma_f32_16x16x32_bf16 v[68:71], v[108:111], v[128:131], v[68:71]
	v_mfma_f32_16x16x32_bf16 v[76:79], v[124:127], v[128:131], v[76:79]
	v_mfma_f32_16x16x32_bf16 v[84:87], v[136:139], v[128:131], v[84:87]
	v_mfma_f32_16x16x32_bf16 v[88:91], v[140:143], v[128:131], v[88:91]
	ds_read_b128 v[128:131], v31 offset:36864
	ds_read_b128 v[144:147], v31 offset:38912
	global_load_lds_dwordx4 v[154:155], off
	s_mov_b32 m0, s19
	v_mfma_f32_16x16x32_bf16 v[92:95], v[108:111], v[132:135], v[92:95]
	global_load_lds_dwordx4 v[162:163], off
	s_mov_b32 m0, s23
	v_mfma_f32_16x16x32_bf16 v[96:99], v[124:127], v[132:135], v[96:99]
	global_load_lds_dwordx4 v[156:157], off
	s_mov_b32 m0, s18
	v_mfma_f32_16x16x32_bf16 v[100:103], v[136:139], v[132:135], v[100:103]
	global_load_lds_dwordx4 v[150:151], off
	s_mov_b32 m0, s22
	v_mfma_f32_16x16x32_bf16 v[64:67], v[140:143], v[132:135], v[64:67]
	global_load_lds_dwordx4 v[158:159], off
	s_mov_b32 m0, s17
	s_waitcnt lgkmcnt(0)
	v_mfma_f32_16x16x32_bf16 v[112:115], v[108:111], v[128:131], v[112:115]
	global_load_lds_dwordx4 v[148:149], off
	s_mov_b32 m0, s21
	v_mfma_f32_16x16x32_bf16 v[116:119], v[124:127], v[128:131], v[116:119]
	global_load_lds_dwordx4 v[160:161], off
	s_waitcnt vmcnt(0)
	v_mfma_f32_16x16x32_bf16 v[120:123], v[136:139], v[128:131], v[120:123]
	s_waitcnt vmcnt(0) lgkmcnt(0)
	s_barrier
; #define MFMA16(a, b, c) __builtin_amdgcn_mfma_f32_16x16x32_bf16((a), (b), (c), 0, 0, 0)
; #define LAS __attribute__((address_space(3)))
; template <class FA, class FB, class FL, class FS>
; DI void gemm_tile(char* lds, int ksteps, int rot, FA fa, FB fb, FL fl, FS fs) {
;     ...
;   for (int ks = 0; ks < ksteps; ++ks) {
;     const int cur = ks & 1;
;     if (ks + 1 < ksteps) {
;       int kn = ks + 1 + rot; if (kn >= ksteps) kn -= ksteps;
;       LAS char* dst = l3 + (cur ^ 1) * 32768;
; #pragma unroll
;       for (int i = 0; i < 4; ++i) {
;         const int id = tid + i * 256, r = id >> 3, c = (id & 7) ^ (r & 7);
;         __builtin_amdgcn_global_load_lds((const unsigned*)fa(r, kn * 8 + c), (LAS unsigned*)(dst + id * 16), 16, 0, 0);
;         __builtin_amdgcn_global_load_lds((const unsigned*)fb(r, kn * 8 + c), (LAS unsigned*)(dst + 16384 + id * 16), 16, 0, 0);
;       }
;     }
;     const char* A = lds + cur * 32768;
;     const char* B = A + 16384;
; #pragma unroll
;     for (int kk = 0; kk < 2; ++kk) {
;       bf16x8 af[4], bq[4];
; #pragma unroll
;       for (int m = 0; m < 4; ++m) af[m] = ldfrag(A, 128, wr * 64 + m * 16 + fr, kk * 4 + fq);
; #pragma unroll
;       for (int n = 0; n < 4; ++n) bq[n] = ldfrag(B, 128, wc * 64 + n * 16 + fr, kk * 4 + fq);
; #pragma unroll
;       for (int m = 0; m < 4; ++m)
; #pragma unroll
;         for (int n = 0; n < 4; ++n) acc[m][n] = MFMA16(bq[n], af[m], acc[m][n]);
;     }
;     asm volatile("s_waitcnt vmcnt(0)" ::: "memory");
;     __syncthreads();
	v_mfma_f32_16x16x32_bf16 v[104:107], v[140:143], v[128:131], v[104:107]
	s_mov_b32 m0, s10
	v_readfirstlane_b32 s10, v42
	v_mfma_f32_16x16x32_bf16 v[56:59], v[108:111], v[144:147], v[56:59]
	v_mfma_f32_16x16x32_bf16 v[60:63], v[124:127], v[144:147], v[60:63]
	ds_read_b128 v[108:111], v32 offset:16384
	ds_read_b128 v[124:127], v32 offset:18432
	ds_read_b128 v[128:131], v30
	ds_read_b128 v[132:135], v30 offset:2048
	v_mfma_f32_16x16x32_bf16 v[72:75], v[136:139], v[144:147], v[72:75]
	ds_read_b128 v[136:139], v32 offset:20480
	v_mfma_f32_16x16x32_bf16 v[80:83], v[140:143], v[144:147], v[80:83]
	ds_read_b128 v[140:143], v32 offset:22528
	v_or_b32_e32 v147, v0, v39
	v_or_b32_e32 v144, v0, v35
	s_waitcnt lgkmcnt(3)
	v_mfma_f32_16x16x32_bf16 v[68:71], v[108:111], v[128:131], v[68:71]
	v_or_b32_e32 v145, v0, v37
	v_lshlrev_b32_e32 v144, 3, v144
	v_lshlrev_b32_e32 v146, 3, v145
	v_mfma_f32_16x16x32_bf16 v[76:79], v[124:127], v[128:131], v[76:79]
	v_ashrrev_i32_e32 v145, 31, v144
	v_lshlrev_b64 v[144:145], 1, v[144:145]
	v_lshl_add_u64 v[152:153], v[10:11], 0, v[144:145]
	s_waitcnt lgkmcnt(1)
	v_mfma_f32_16x16x32_bf16 v[84:87], v[136:139], v[128:131], v[84:87]
	v_lshl_add_u64 v[154:155], v[12:13], 0, v[144:145]
	v_or_b32_e32 v0, v0, v38
	v_lshlrev_b32_e32 v148, 3, v0
	s_waitcnt lgkmcnt(0)
	v_mfma_f32_16x16x32_bf16 v[88:91], v[140:143], v[128:131], v[88:91]
	v_ashrrev_i32_e32 v149, 31, v148
	v_lshlrev_b64 v[148:149], 1, v[148:149]
	v_lshl_add_u64 v[160:161], v[4:5], 0, v[148:149]
	v_mfma_f32_16x16x32_bf16 v[92:95], v[108:111], v[132:135], v[92:95]
	v_lshl_add_u64 v[148:149], v[18:19], 0, v[148:149]
	v_cndmask_b32_e64 v0, 48, -16, vcc
	v_add_u32_e32 v0, v0, v52
	v_mfma_f32_16x16x32_bf16 v[96:99], v[124:127], v[132:135], v[96:99]
	v_or_b32_e32 v42, v0, v39
	v_or_b32_e32 v36, v0, v35
	v_cmp_ne_u32_e32 vcc, 0, v34
	v_mfma_f32_16x16x32_bf16 v[100:103], v[136:139], v[132:135], v[100:103]
	v_mfma_f32_16x16x32_bf16 v[64:67], v[140:143], v[132:135], v[64:67]
	ds_read_b128 v[128:131], v30 offset:4096
	ds_read_b128 v[132:135], v30 offset:6144
	s_waitcnt lgkmcnt(1)
	v_mfma_f32_16x16x32_bf16 v[112:115], v[108:111], v[128:131], v[112:115]
	v_mfma_f32_16x16x32_bf16 v[116:119], v[124:127], v[128:131], v[116:119]
	v_mfma_f32_16x16x32_bf16 v[120:123], v[136:139], v[128:131], v[120:123]
	v_mfma_f32_16x16x32_bf16 v[104:107], v[140:143], v[128:131], v[104:107]
	v_lshlrev_b32_e32 v128, 3, v147
	v_ashrrev_i32_e32 v129, 31, v128
	v_lshlrev_b64 v[150:151], 1, v[128:129]
	s_waitcnt lgkmcnt(0)
	v_mfma_f32_16x16x32_bf16 v[56:59], v[108:111], v[132:135], v[56:59]
	v_ashrrev_i32_e32 v147, 31, v146
	v_lshlrev_b64 v[146:147], 1, v[146:147]
	v_lshl_add_u64 v[156:157], v[6:7], 0, v[146:147]
	v_mfma_f32_16x16x32_bf16 v[60:63], v[124:127], v[132:135], v[60:63]
	ds_read_b128 v[108:111], v33 offset:16384
	ds_read_b128 v[124:127], v33 offset:18432
	v_lshl_add_u64 v[162:163], v[14:15], 0, v[146:147]
	v_lshl_add_u64 v[158:159], v[8:9], 0, v[150:151]
	v_mfma_f32_16x16x32_bf16 v[72:75], v[136:139], v[132:135], v[72:75]
	v_lshl_add_u64 v[150:151], v[16:17], 0, v[150:151]
	v_mfma_f32_16x16x32_bf16 v[80:83], v[140:143], v[132:135], v[80:83]
	ds_read_b128 v[128:131], v31
	ds_read_b128 v[132:135], v31 offset:2048
	ds_read_b128 v[136:139], v33 offset:20480
	ds_read_b128 v[140:143], v33 offset:22528
	global_load_lds_dwordx4 v[152:153], off
	s_mov_b32 m0, s3
	s_waitcnt lgkmcnt(0)
	v_mfma_f32_16x16x32_bf16 v[68:71], v[108:111], v[128:131], v[68:71]
	v_readfirstlane_b32 s3, v41
	v_or_b32_e32 v41, v0, v37
	v_or_b32_e32 v0, v0, v38
	v_mfma_f32_16x16x32_bf16 v[76:79], v[124:127], v[128:131], v[76:79]
	v_mfma_f32_16x16x32_bf16 v[84:87], v[136:139], v[128:131], v[84:87]
	v_mfma_f32_16x16x32_bf16 v[88:91], v[140:143], v[128:131], v[88:91]
	ds_read_b128 v[128:131], v31 offset:4096
	ds_read_b128 v[144:147], v31 offset:6144
	global_load_lds_dwordx4 v[154:155], off
	s_mov_b32 m0, s16
	v_mfma_f32_16x16x32_bf16 v[92:95], v[108:111], v[132:135], v[92:95]
	global_load_lds_dwordx4 v[162:163], off
	s_mov_b32 m0, s15
	v_mfma_f32_16x16x32_bf16 v[96:99], v[124:127], v[132:135], v[96:99]
	global_load_lds_dwordx4 v[156:157], off
	s_mov_b32 m0, s14
	v_mfma_f32_16x16x32_bf16 v[100:103], v[136:139], v[132:135], v[100:103]
	global_load_lds_dwordx4 v[150:151], off
	s_mov_b32 m0, s13
	v_mfma_f32_16x16x32_bf16 v[64:67], v[140:143], v[132:135], v[64:67]
	global_load_lds_dwordx4 v[158:159], off
	s_mov_b32 m0, s12
	s_waitcnt lgkmcnt(0)
	v_mfma_f32_16x16x32_bf16 v[112:115], v[108:111], v[128:131], v[112:115]
	global_load_lds_dwordx4 v[148:149], off
	s_mov_b32 m0, s11
	v_mfma_f32_16x16x32_bf16 v[116:119], v[124:127], v[128:131], v[116:119]
	global_load_lds_dwordx4 v[160:161], off
	s_waitcnt vmcnt(0)
	v_mfma_f32_16x16x32_bf16 v[120:123], v[136:139], v[128:131], v[120:123]
	s_waitcnt vmcnt(0) lgkmcnt(0)
	s_barrier
; #define MFMA16(a, b, c) __builtin_amdgcn_mfma_f32_16x16x32_bf16((a), (b), (c), 0, 0, 0)
; #define LAS __attribute__((address_space(3)))
; template <class FA, class FB, class FL, class FS>
; DI void gemm_tile(char* lds, int ksteps, int rot, FA fa, FB fb, FL fl, FS fs) {
;     ...
;   for (int ks = 0; ks < ksteps; ++ks) {
;     const int cur = ks & 1;
;     if (ks + 1 < ksteps) {
;       int kn = ks + 1 + rot; if (kn >= ksteps) kn -= ksteps;
;       LAS char* dst = l3 + (cur ^ 1) * 32768;
; #pragma unroll
;       for (int i = 0; i < 4; ++i) {
;         const int id = tid + i * 256, r = id >> 3, c = (id & 7) ^ (r & 7);
;         __builtin_amdgcn_global_load_lds((const unsigned*)fa(r, kn * 8 + c), (LAS unsigned*)(dst + id * 16), 16, 0, 0);
;         __builtin_amdgcn_global_load_lds((const unsigned*)fb(r, kn * 8 + c), (LAS unsigned*)(dst + 16384 + id * 16), 16, 0, 0);
;       }
;     }
;     const char* A = lds + cur * 32768;
;     const char* B = A + 16384;
; #pragma unroll
;     for (int kk = 0; kk < 2; ++kk) {
;       bf16x8 af[4], bq[4];
; #pragma unroll
;       for (int m = 0; m < 4; ++m) af[m] = ldfrag(A, 128, wr * 64 + m * 16 + fr, kk * 4 + fq);
; #pragma unroll
;       for (int n = 0; n < 4; ++n) bq[n] = ldfrag(B, 128, wc * 64 + n * 16 + fr, kk * 4 + fq);
; #pragma unroll
;       for (int m = 0; m < 4; ++m)
; #pragma unroll
;         for (int n = 0; n < 4; ++n) acc[m][n] = MFMA16(bq[n], af[m], acc[m][n]);
;     }
;     asm volatile("s_waitcnt vmcnt(0)" ::: "memory");
;     __syncthreads();
	v_mfma_f32_16x16x32_bf16 v[104:107], v[140:143], v[128:131], v[104:107]
	v_readfirstlane_b32 s13, v54
	v_readfirstlane_b32 s15, v55
	v_readfirstlane_b32 s11, v44
	v_mfma_f32_16x16x32_bf16 v[56:59], v[108:111], v[144:147], v[56:59]
	v_lshlrev_b32_e32 v44, 3, v36
	v_readfirstlane_b32 s12, v45
	v_ashrrev_i32_e32 v45, 31, v44
	v_mfma_f32_16x16x32_bf16 v[60:63], v[124:127], v[144:147], v[60:63]
	ds_read_b128 v[108:111], v32 offset:49152
	ds_read_b128 v[124:127], v32 offset:51200
	ds_read_b128 v[128:131], v30 offset:32768
	ds_read_b128 v[132:135], v30 offset:34816
	v_lshlrev_b64 v[44:45], 1, v[44:45]
	v_mfma_f32_16x16x32_bf16 v[72:75], v[136:139], v[144:147], v[72:75]
	ds_read_b128 v[136:139], v32 offset:53248
	v_lshl_add_u64 v[148:149], v[10:11], 0, v[44:45]
	s_mov_b32 m0, s2
	v_mfma_f32_16x16x32_bf16 v[80:83], v[140:143], v[144:147], v[80:83]
	ds_read_b128 v[140:143], v32 offset:55296
	v_lshlrev_b32_e32 v144, 3, v41
	v_ashrrev_i32_e32 v145, 31, v144
	s_waitcnt lgkmcnt(3)
	v_mfma_f32_16x16x32_bf16 v[68:71], v[108:111], v[128:131], v[68:71]
	v_lshlrev_b32_e32 v146, 3, v0
	v_ashrrev_i32_e32 v147, 31, v146
	v_lshlrev_b64 v[146:147], 1, v[146:147]
	v_mfma_f32_16x16x32_bf16 v[76:79], v[124:127], v[128:131], v[76:79]
	v_lshl_add_u64 v[44:45], v[12:13], 0, v[44:45]
	v_lshl_add_u64 v[154:155], v[4:5], 0, v[146:147]
	v_lshl_add_u64 v[160:161], v[18:19], 0, v[146:147]
	s_waitcnt lgkmcnt(1)
	v_mfma_f32_16x16x32_bf16 v[84:87], v[136:139], v[128:131], v[84:87]
	v_readfirstlane_b32 s14, v53
	v_readfirstlane_b32 s2, v40
	v_add_u32_e32 v0, -8, v52
	s_waitcnt lgkmcnt(0)
	v_mfma_f32_16x16x32_bf16 v[88:91], v[140:143], v[128:131], v[88:91]
	v_cndmask_b32_e32 v0, 56, v0, vcc
	v_or_b32_e32 v53, v0, v37
	v_or_b32_e32 v39, v0, v39
	v_mfma_f32_16x16x32_bf16 v[92:95], v[108:111], v[132:135], v[92:95]
	v_or_b32_e32 v52, v0, v35
	v_or_b32_e32 v0, v0, v38
	v_lshlrev_b32_e32 v38, 3, v52
	v_mfma_f32_16x16x32_bf16 v[96:99], v[124:127], v[132:135], v[96:99]
	v_mfma_f32_16x16x32_bf16 v[100:103], v[136:139], v[132:135], v[100:103]
	v_mfma_f32_16x16x32_bf16 v[64:67], v[140:143], v[132:135], v[64:67]
	ds_read_b128 v[128:131], v30 offset:36864
	ds_read_b128 v[132:135], v30 offset:38912
	s_waitcnt lgkmcnt(1)
	v_mfma_f32_16x16x32_bf16 v[112:115], v[108:111], v[128:131], v[112:115]
	v_mfma_f32_16x16x32_bf16 v[116:119], v[124:127], v[128:131], v[116:119]
	v_mfma_f32_16x16x32_bf16 v[120:123], v[136:139], v[128:131], v[120:123]
	v_mfma_f32_16x16x32_bf16 v[104:107], v[140:143], v[128:131], v[104:107]
	v_lshlrev_b32_e32 v128, 3, v42
	v_ashrrev_i32_e32 v129, 31, v128
	s_waitcnt lgkmcnt(0)
	v_mfma_f32_16x16x32_bf16 v[54:57], v[108:111], v[132:135], v[56:59]
	v_mfma_f32_16x16x32_bf16 v[58:61], v[124:127], v[132:135], v[60:63]
	ds_read_b128 v[108:111], v33 offset:49152
	ds_read_b128 v[124:127], v33 offset:51200
	s_nop 0
	v_lshlrev_b64 v[62:63], 1, v[144:145]
	v_lshlrev_b64 v[144:145], 1, v[128:129]
	v_mfma_f32_16x16x32_bf16 v[72:75], v[136:139], v[132:135], v[72:75]
	v_lshl_add_u64 v[152:153], v[8:9], 0, v[144:145]
	v_lshl_add_u64 v[156:157], v[14:15], 0, v[62:63]
	v_lshl_add_u64 v[158:159], v[16:17], 0, v[144:145]
	v_mfma_f32_16x16x32_bf16 v[80:83], v[140:143], v[132:135], v[80:83]
	ds_read_b128 v[128:131], v31 offset:32768
	ds_read_b128 v[132:135], v31 offset:34816
	ds_read_b128 v[136:139], v33 offset:53248
	ds_read_b128 v[140:143], v33 offset:55296
	global_load_lds_dwordx4 v[148:149], off
	s_mov_b32 m0, s3
	s_waitcnt lgkmcnt(0)
	v_mfma_f32_16x16x32_bf16 v[68:71], v[108:111], v[128:131], v[68:71]
	v_lshl_add_u64 v[150:151], v[6:7], 0, v[62:63]
	v_readfirstlane_b32 s3, v43
	v_mfma_f32_16x16x32_bf16 v[76:79], v[124:127], v[128:131], v[76:79]
	v_mfma_f32_16x16x32_bf16 v[84:87], v[136:139], v[128:131], v[84:87]
	v_mfma_f32_16x16x32_bf16 v[88:91], v[140:143], v[128:131], v[88:91]
	ds_read_b128 v[128:131], v31 offset:36864
	ds_read_b128 v[144:147], v31 offset:38912
	global_load_lds_dwordx4 v[44:45], off
	s_mov_b32 m0, s10
	v_mfma_f32_16x16x32_bf16 v[92:95], v[108:111], v[132:135], v[92:95]
	global_load_lds_dwordx4 v[156:157], off
	s_mov_b32 m0, s13
	v_mfma_f32_16x16x32_bf16 v[96:99], v[124:127], v[132:135], v[96:99]
	global_load_lds_dwordx4 v[150:151], off
	s_mov_b32 m0, s11
	v_mfma_f32_16x16x32_bf16 v[100:103], v[136:139], v[132:135], v[100:103]
	global_load_lds_dwordx4 v[158:159], off
	s_mov_b32 m0, s14
	v_mfma_f32_16x16x32_bf16 v[62:65], v[140:143], v[132:135], v[64:67]
	global_load_lds_dwordx4 v[152:153], off
	s_mov_b32 m0, s12
	s_waitcnt lgkmcnt(0)
	v_mfma_f32_16x16x32_bf16 v[112:115], v[108:111], v[128:131], v[112:115]
	global_load_lds_dwordx4 v[160:161], off
	s_mov_b32 m0, s15
	v_mfma_f32_16x16x32_bf16 v[116:119], v[124:127], v[128:131], v[116:119]
	global_load_lds_dwordx4 v[154:155], off
	s_waitcnt vmcnt(0)
	v_mfma_f32_16x16x32_bf16 v[120:123], v[136:139], v[128:131], v[120:123]
	s_waitcnt vmcnt(0) lgkmcnt(0)
	s_barrier
; #define MFMA16(a, b, c) __builtin_amdgcn_mfma_f32_16x16x32_bf16((a), (b), (c), 0, 0, 0)
; #define LAS __attribute__((address_space(3)))
; template <class FA, class FB, class FL, class FS>
; DI void gemm_tile(char* lds, int ksteps, int rot, FA fa, FB fb, FL fl, FS fs) {
;     ...
;   for (int ks = 0; ks < ksteps; ++ks) {
;     const int cur = ks & 1;
;     if (ks + 1 < ksteps) {
;       int kn = ks + 1 + rot; if (kn >= ksteps) kn -= ksteps;
;       LAS char* dst = l3 + (cur ^ 1) * 32768;
; #pragma unroll
;       for (int i = 0; i < 4; ++i) {
;         const int id = tid + i * 256, r = id >> 3, c = (id & 7) ^ (r & 7);
;         __builtin_amdgcn_global_load_lds((const unsigned*)fa(r, kn * 8 + c), (LAS unsigned*)(dst + id * 16), 16, 0, 0);
;         __builtin_amdgcn_global_load_lds((const unsigned*)fb(r, kn * 8 + c), (LAS unsigned*)(dst + 16384 + id * 16), 16, 0, 0);
;       }
;     }
;     const char* A = lds + cur * 32768;
;     const char* B = A + 16384;
; #pragma unroll
;     for (int kk = 0; kk < 2; ++kk) {
;       bf16x8 af[4], bq[4];
; #pragma unroll
;       for (int m = 0; m < 4; ++m) af[m] = ldfrag(A, 128, wr * 64 + m * 16 + fr, kk * 4 + fq);
; #pragma unroll
;       for (int n = 0; n < 4; ++n) bq[n] = ldfrag(B, 128, wc * 64 + n * 16 + fr, kk * 4 + fq);
; #pragma unroll
;       for (int m = 0; m < 4; ++m)
; #pragma unroll
;         for (int n = 0; n < 4; ++n) acc[m][n] = MFMA16(bq[n], af[m], acc[m][n]);
;     }
;     asm volatile("s_waitcnt vmcnt(0)" ::: "memory");
;     __syncthreads();
	v_mfma_f32_16x16x32_bf16 v[104:107], v[140:143], v[128:131], v[104:107]
	v_readfirstlane_b32 s12, v50
	v_readfirstlane_b32 s13, v48
	v_readfirstlane_b32 s14, v49
	v_mfma_f32_16x16x32_bf16 v[54:57], v[108:111], v[144:147], v[54:57]
	v_readfirstlane_b32 s15, v51
	v_readfirstlane_b32 s10, v46
	v_readfirstlane_b32 s11, v47
	v_mfma_f32_16x16x32_bf16 v[58:61], v[124:127], v[144:147], v[58:61]
	ds_read_b128 v[108:111], v32 offset:16384
	ds_read_b128 v[124:127], v32 offset:18432
	ds_read_b128 v[128:131], v30
	ds_read_b128 v[132:135], v30 offset:2048
	s_mov_b32 m0, s2
	v_mfma_f32_16x16x32_bf16 v[72:75], v[136:139], v[144:147], v[72:75]
	ds_read_b128 v[136:139], v32 offset:20480
	s_mul_i32 s2, s1, s25
	v_mfma_f32_16x16x32_bf16 v[80:83], v[140:143], v[144:147], v[80:83]
	ds_read_b128 v[140:143], v32 offset:22528
	s_waitcnt lgkmcnt(2)
	v_mfma_f32_16x16x32_bf16 v[40:43], v[124:127], v[132:135], v[96:99]
	s_waitcnt lgkmcnt(0)
	v_mfma_f32_16x16x32_bf16 v[48:51], v[140:143], v[132:135], v[62:65]
	s_nop 2
	ds_read_b128 v[62:65], v30 offset:4096
	ds_read_b128 v[96:99], v30 offset:6144
	v_mfma_f32_16x16x32_bf16 v[66:69], v[108:111], v[128:131], v[68:71]
	v_mfma_f32_16x16x32_bf16 v[44:47], v[136:139], v[132:135], v[100:103]
	s_nop 1
	v_lshlrev_b32_e32 v70, 3, v53
	v_ashrrev_i32_e32 v71, 31, v70
	s_waitcnt lgkmcnt(1)
	v_mfma_f32_16x16x32_bf16 v[100:103], v[108:111], v[62:65], v[112:115]
	v_mfma_f32_16x16x32_bf16 v[112:115], v[124:127], v[62:65], v[116:119]
	v_mfma_f32_16x16x32_bf16 v[34:37], v[136:139], v[62:65], v[120:123]
	v_mfma_f32_16x16x32_bf16 v[62:65], v[140:143], v[62:65], v[104:107]
	s_nop 2
	v_lshlrev_b32_e32 v104, 3, v39
	v_ashrrev_i32_e32 v105, 31, v104
	v_mfma_f32_16x16x32_bf16 v[76:79], v[124:127], v[128:131], v[76:79]
	v_ashrrev_i32_e32 v39, 31, v38
	v_lshlrev_b64 v[38:39], 1, v[38:39]
	v_mfma_f32_16x16x32_bf16 v[84:87], v[136:139], v[128:131], v[84:87]
	v_mfma_f32_16x16x32_bf16 v[88:91], v[140:143], v[128:131], v[88:91]
	v_lshlrev_b64 v[130:131], 1, v[104:105]
	v_lshlrev_b32_e32 v128, 3, v0
	v_ashrrev_i32_e32 v129, 31, v128
	v_mfma_f32_16x16x32_bf16 v[92:95], v[108:111], v[132:135], v[92:95]
	v_lshl_add_u64 v[132:133], v[12:13], 0, v[38:39]
	v_lshl_add_u64 v[134:135], v[8:9], 0, v[130:131]
	v_lshl_add_u64 v[130:131], v[16:17], 0, v[130:131]
	s_waitcnt lgkmcnt(0)
	v_mfma_f32_16x16x32_bf16 v[52:55], v[108:111], v[96:99], v[54:57]
	ds_read_b128 v[104:107], v33 offset:16384
	ds_read_b128 v[108:111], v33 offset:18432
	v_lshl_or_b32 v0, v27, 6, v26
	v_mfma_f32_16x16x32_bf16 v[56:59], v[124:127], v[96:99], v[58:61]
	s_nop 2
	v_lshlrev_b64 v[60:61], 1, v[70:71]
	v_mfma_f32_16x16x32_bf16 v[70:73], v[136:139], v[96:99], v[72:75]
	v_mfma_f32_16x16x32_bf16 v[80:83], v[140:143], v[96:99], v[80:83]
	ds_read_b128 v[96:99], v31
	ds_read_b128 v[116:119], v31 offset:2048
	ds_read_b128 v[120:123], v33 offset:20480
	ds_read_b128 v[124:127], v33 offset:22528
	s_waitcnt lgkmcnt(3)
	v_mfma_f32_16x16x32_bf16 v[74:77], v[108:111], v[96:99], v[76:79]
	s_nop 2
	v_lshlrev_b64 v[78:79], 1, v[128:129]
	v_lshl_add_u64 v[128:129], v[10:11], 0, v[38:39]
	global_load_lds_dwordx4 v[128:129], off
	s_mov_b32 m0, s3
	v_mfma_f32_16x16x32_bf16 v[66:69], v[104:107], v[96:99], v[66:69]
	v_lshl_add_u64 v[18:19], v[18:19], 0, v[78:79]
	v_lshl_add_u64 v[4:5], v[4:5], 0, v[78:79]
	s_waitcnt lgkmcnt(0)
	v_mfma_f32_16x16x32_bf16 v[84:87], v[120:123], v[96:99], v[84:87]
	v_mfma_f32_16x16x32_bf16 v[10:13], v[124:127], v[96:99], v[88:91]
	v_lshl_add_u64 v[96:97], v[14:15], 0, v[60:61]
	v_lshl_add_u64 v[60:61], v[6:7], 0, v[60:61]
	v_mfma_f32_16x16x32_bf16 v[14:17], v[108:111], v[116:119], v[40:43]
	s_nop 2
	ds_read_b128 v[38:41], v31 offset:4096
	ds_read_b128 v[88:91], v31 offset:6144
	global_load_lds_dwordx4 v[132:133], off
	s_mov_b32 m0, s10
	v_mfma_f32_16x16x32_bf16 v[6:9], v[104:107], v[116:119], v[92:95]
	global_load_lds_dwordx4 v[96:97], off
	s_mov_b32 m0, s11
	v_mfma_f32_16x16x32_bf16 v[42:45], v[120:123], v[116:119], v[44:47]
	global_load_lds_dwordx4 v[60:61], off
	s_mov_b32 m0, s12
	v_mfma_f32_16x16x32_bf16 v[46:49], v[124:127], v[116:119], v[48:51]
	global_load_lds_dwordx4 v[130:131], off
	s_mov_b32 m0, s13
	s_waitcnt lgkmcnt(0)
	v_mfma_f32_16x16x32_bf16 v[92:95], v[104:107], v[38:41], v[100:103]
	global_load_lds_dwordx4 v[134:135], off
	s_mov_b32 m0, s14
	v_mfma_f32_16x16x32_bf16 v[96:99], v[108:111], v[38:41], v[112:115]
	global_load_lds_dwordx4 v[18:19], off
	s_mov_b32 m0, s15
	v_mfma_f32_16x16x32_bf16 v[34:37], v[120:123], v[38:41], v[34:37]
	global_load_lds_dwordx4 v[4:5], off
	s_waitcnt vmcnt(0)
	v_mfma_f32_16x16x32_bf16 v[38:41], v[124:127], v[38:41], v[62:65]
	s_waitcnt vmcnt(0) lgkmcnt(0)
	s_barrier
; #define MFMA16(a, b, c) __builtin_amdgcn_mfma_f32_16x16x32_bf16((a), (b), (c), 0, 0, 0)
; template <class FA, class FB, class FL, class FS>
; DI void gemm_tile(char* lds, int ksteps, int rot, FA fa, FB fb, FL fl, FS fs) {
;     ...
; #pragma unroll
;     for (int kk = 0; kk < 2; ++kk) {
;       bf16x8 af[4], bq[4];
; #pragma unroll
;       for (int m = 0; m < 4; ++m) af[m] = ldfrag(A, 128, wr * 64 + m * 16 + fr, kk * 4 + fq);
; #pragma unroll
;       for (int n = 0; n < 4; ++n) bq[n] = ldfrag(B, 128, wc * 64 + n * 16 + fr, kk * 4 + fq);
; #pragma unroll
;       for (int m = 0; m < 4; ++m)
; #pragma unroll
;         for (int n = 0; n < 4; ++n) acc[m][n] = MFMA16(bq[n], af[m], acc[m][n]);
;     }
;     asm volatile("s_waitcnt vmcnt(0)" ::: "memory");
;     __syncthreads();
;   }
;   decltype(fl(0, 0)) ld[4][4];
; #pragma unroll
;   for (int m = 0; m < 4; ++m)
; #pragma unroll
;     for (int n = 0; n < 4; ++n) ld[m][n] = fl(wr * 64 + m * 16 + fr, wc * 64 + n * 16 + 4 * fq);
; #pragma unroll
;   for (int m = 0; m < 4; ++m)
; #pragma unroll
;     for (int n = 0; n < 4; ++n) fs(wr * 64 + m * 16 + fr, wc * 64 + n * 16 + 4 * fq, acc[m][n], ld[m][n]);
; DI void xcd_barrier(const XcdBarrier& b) {
;   asm volatile("s_waitcnt vmcnt(0)" ::: "memory");
;   __syncthreads();
;   if (threadIdx.x == 0) {
;     unsigned* bar = b.bar;
;     __builtin_amdgcn_s_waitcnt(0);
;     unsigned nloc = b.st[0], nx = b.st[1];
;     if (nloc == 0u) { xcd_barrier_complete(bar, b.x, nloc, nx); b.st[0] = nloc; b.st[1] = nx; }
	v_mfma_f32_16x16x32_bf16 v[50:53], v[104:107], v[88:91], v[52:55]
	ds_read_b128 v[62:65], v32 offset:49152
	ds_read_b128 v[100:103], v32 offset:53248
	ds_read_b128 v[104:107], v32 offset:55296
	v_mfma_f32_16x16x32_bf16 v[54:57], v[108:111], v[88:91], v[56:59]
	v_lshlrev_b32_e32 v18, 7, v29
	v_or3_b32 v2, v0, v18, v2
	v_lshlrev_b64 v[108:109], 9, v[2:3]
	v_mfma_f32_16x16x32_bf16 v[58:61], v[120:123], v[88:91], v[70:73]
	v_mfma_f32_16x16x32_bf16 v[70:73], v[124:127], v[88:91], v[80:83]
	ds_read_b128 v[88:91], v32 offset:51200
	s_nop 1
	ds_read_b128 v[78:81], v30 offset:32768
	s_waitcnt lgkmcnt(0)
	v_mfma_f32_16x16x32_bf16 v[66:69], v[62:65], v[78:81], v[66:69]
	v_or_b32_e32 v32, 16, v2
	v_mfma_f32_16x16x32_bf16 v[74:77], v[88:91], v[78:81], v[74:77]
	v_mfma_f32_16x16x32_bf16 v[82:85], v[100:103], v[78:81], v[84:87]
	v_mfma_f32_16x16x32_bf16 v[10:13], v[104:107], v[78:81], v[10:13]
	ds_read_b128 v[78:81], v30 offset:34816
	s_waitcnt lgkmcnt(0)
	v_mfma_f32_16x16x32_bf16 v[4:7], v[62:65], v[78:81], v[6:9]
	v_mfma_f32_16x16x32_bf16 v[14:17], v[88:91], v[78:81], v[14:17]
	v_mfma_f32_16x16x32_bf16 v[42:45], v[100:103], v[78:81], v[42:45]
	v_mfma_f32_16x16x32_bf16 v[46:49], v[104:107], v[78:81], v[46:49]
	ds_read_b128 v[78:81], v30 offset:36864
	s_waitcnt lgkmcnt(0)
	v_mfma_f32_16x16x32_bf16 v[92:95], v[62:65], v[78:81], v[92:95]
	v_mfma_f32_16x16x32_bf16 v[96:99], v[88:91], v[78:81], v[96:99]
	v_mfma_f32_16x16x32_bf16 v[34:37], v[100:103], v[78:81], v[34:37]
	v_mfma_f32_16x16x32_bf16 v[38:41], v[104:107], v[78:81], v[38:41]
	ds_read_b128 v[78:81], v30 offset:38912
	v_lshlrev_b32_e32 v30, 4, v28
	v_lshl_or_b32 v0, v25, 8, v30
	s_waitcnt lgkmcnt(0)
	v_mfma_f32_16x16x32_bf16 v[50:53], v[62:65], v[78:81], v[50:53]
	ds_read_b128 v[62:65], v33 offset:49152
	v_mfma_f32_16x16x32_bf16 v[54:57], v[88:91], v[78:81], v[54:57]
	ds_read_b128 v[86:89], v33 offset:51200
	v_mov_b32_e32 v91, v3
	v_or_b32_e32 v90, 32, v2
	v_mfma_f32_16x16x32_bf16 v[58:61], v[100:103], v[78:81], v[58:61]
	ds_read_b128 v[100:103], v33 offset:53248
	v_or_b32_e32 v2, 48, v2
	v_lshlrev_b64 v[90:91], 9, v[90:91]
	v_mfma_f32_16x16x32_bf16 v[70:73], v[104:107], v[78:81], v[70:73]
	ds_read_b128 v[104:107], v33 offset:55296
	ds_read_b128 v[78:81], v31 offset:32768
	v_mov_b32_e32 v33, v3
	s_waitcnt lgkmcnt(0)
	v_mfma_f32_16x16x32_bf16 v[66:69], v[62:65], v[78:81], v[66:69]
	v_lshlrev_b64 v[2:3], 9, v[2:3]
	v_lshl_add_u64 v[90:91], s[8:9], 0, v[90:91]
	v_lshl_add_u64 v[2:3], s[8:9], 0, v[2:3]
	v_mfma_f32_16x16x32_bf16 v[74:77], v[86:89], v[78:81], v[74:77]
	v_lshl_add_u64 v[2:3], v[2:3], 0, v[0:1]
	v_mfma_f32_16x16x32_bf16 v[82:85], v[100:103], v[78:81], v[82:85]
	v_mfma_f32_16x16x32_bf16 v[8:11], v[104:107], v[78:81], v[10:13]
	ds_read_b128 v[78:81], v31 offset:34816
	s_waitcnt lgkmcnt(0)
	v_mfma_f32_16x16x32_bf16 v[12:15], v[86:89], v[78:81], v[14:17]
	v_mfma_f32_16x16x32_bf16 v[16:19], v[100:103], v[78:81], v[42:45]
	s_nop 2
	ds_read_b128 v[42:45], v31 offset:36864
	v_mfma_f32_16x16x32_bf16 v[4:7], v[62:65], v[78:81], v[4:7]
	v_mfma_f32_16x16x32_bf16 v[26:29], v[104:107], v[78:81], v[46:49]
	s_waitcnt lgkmcnt(0)
	v_mfma_f32_16x16x32_bf16 v[46:49], v[62:65], v[42:45], v[92:95]
	v_mfma_f32_16x16x32_bf16 v[78:81], v[86:89], v[42:45], v[96:99]
	s_nop 1
	v_lshlrev_b64 v[94:95], 9, v[32:33]
	v_lshl_add_u64 v[92:93], s[8:9], 0, v[108:109]
	v_lshl_add_u64 v[94:95], s[8:9], 0, v[94:95]
	v_mfma_f32_16x16x32_bf16 v[32:35], v[100:103], v[42:45], v[34:37]
	v_mfma_f32_16x16x32_bf16 v[36:39], v[104:107], v[42:45], v[38:41]
	v_lshl_add_u64 v[44:45], v[94:95], 0, v[0:1]
	s_nop 1
	ds_read_b128 v[40:43], v31 offset:38912
	s_waitcnt vmcnt(0)
	v_lshl_add_u64 v[30:31], v[92:93], 0, v[0:1]
	s_waitcnt lgkmcnt(0)
	v_mfma_f32_16x16x32_bf16 v[50:53], v[62:65], v[40:43], v[50:53]
	v_lshl_add_u64 v[62:63], v[90:91], 0, v[0:1]
	s_barrier
	v_mfma_f32_16x16x32_bf16 v[54:57], v[86:89], v[40:43], v[54:57]
	v_mfma_f32_16x16x32_bf16 v[58:61], v[100:103], v[40:43], v[58:61]
	v_mfma_f32_16x16x32_bf16 v[40:43], v[104:107], v[40:43], v[70:73]
	global_store_dwordx4 v[30:31], v[66:69], off
	global_store_dwordx4 v[30:31], v[74:77], off offset:64
	global_store_dwordx4 v[30:31], v[82:85], off offset:128
	global_store_dwordx4 v[30:31], v[8:11], off offset:192
	global_store_dwordx4 v[44:45], v[4:7], off
	global_store_dwordx4 v[44:45], v[12:15], off offset:64
	global_store_dwordx4 v[44:45], v[16:19], off offset:128
	global_store_dwordx4 v[44:45], v[26:29], off offset:192
	global_store_dwordx4 v[62:63], v[46:49], off
	global_store_dwordx4 v[62:63], v[78:81], off offset:64
	global_store_dwordx4 v[62:63], v[32:35], off offset:128
	global_store_dwordx4 v[62:63], v[36:39], off offset:192
	global_store_dwordx4 v[2:3], v[50:53], off
	global_store_dwordx4 v[2:3], v[54:57], off offset:64
	global_store_dwordx4 v[2:3], v[58:61], off offset:128
	global_store_dwordx4 v[2:3], v[40:43], off offset:192
	s_cbranch_scc1 .LBB0_513
	s_mov_b32 s0, 0
	s_getreg_b32 s2, hwreg(HW_REG_XCC_ID, 0, 4)
	s_waitcnt vmcnt(0)
	s_barrier
	s_mov_b64 s[4:5], exec
	v_readlane_b32 s6, v251, 5
	v_readlane_b32 s7, v251, 6
	s_and_b64 s[6:7], s[4:5], s[6:7]
	s_mov_b64 exec, s[6:7]
	s_cbranch_execz .LBB0_566
	s_ashr_i32 s1, s0, 31
	v_readlane_b32 s6, v251, 3
	v_readlane_b32 s7, v251, 4
	s_add_u32 s0, s6, s0
	s_addc_u32 s1, s7, s1
	v_mov_b32_e32 v0, 0x20800
	s_load_dwordx2 s[0:1], s[0:1], 0xf8
	s_waitcnt vmcnt(0) expcnt(0) lgkmcnt(0)
	v_mov_b32_e32 v2, v252
	v_mov_b32_e32 v0, 0x20804
	v_mov_b32_e32 v0, v253
	s_and_b32 s33, s2, 15
	s_waitcnt lgkmcnt(1)
	v_cmp_ne_u32_e32 vcc, 0, v2
	s_cbranch_vccnz .LBB0_530
	s_add_u32 s2, s0, 0x16a4300
	s_addc_u32 s3, s1, 0
	s_add_u32 s6, s0, 0x16a4500
	s_addc_u32 s7, s1, 0
	s_add_u32 s8, s0, 0x16a4600
	s_addc_u32 s9, s1, 0
	s_add_u32 s10, s0, 0x16a4700
	s_addc_u32 s11, s1, 0
	s_add_u32 s12, s0, 0x16a4800
	s_addc_u32 s13, s1, 0
	s_add_u32 s14, s0, 0x16a4900
	s_addc_u32 s15, s1, 0
	s_add_u32 s16, s0, 0x16a4a00
	s_addc_u32 s17, s1, 0
	s_add_u32 s18, s0, 0x16a4b00
	s_addc_u32 s19, s1, 0
	s_add_u32 s20, s0, 0x16a4c00
	s_addc_u32 s21, s1, 0
	s_add_u32 s22, s0, 0x16a4d00
	s_addc_u32 s23, s1, 0
	s_add_u32 s24, s0, 0x16a4e00
	s_addc_u32 s25, s1, 0
	s_add_u32 s26, s0, 0x16a4f00
	s_addc_u32 s27, s1, 0
	s_add_u32 s28, s0, 0x16a5000
	s_addc_u32 s29, s1, 0
	s_add_u32 s30, s0, 0x16a5100
	s_addc_u32 s31, s1, 0
	s_add_u32 s34, s0, 0x16a5200
	s_addc_u32 s35, s1, 0
	s_add_u32 s36, s0, 0x16a5300
	s_addc_u32 s37, s1, 0
	s_add_u32 s38, s0, 0x16a5400
	s_addc_u32 s39, s1, 0
	s_mov_b32 s46, 1
	v_mov_b32_e32 v16, 0
	s_branch .LBB0_518

; DI void xcd_barrier(const XcdBarrier& b) {
;   asm volatile("s_waitcnt vmcnt(0)" ::: "memory");
;   __syncthreads();
;   if (threadIdx.x == 0) {
;     unsigned* bar = b.bar;
;     __builtin_amdgcn_s_waitcnt(0);
;     unsigned nloc = b.st[0], nx = b.st[1];
;     if (nloc == 0u) { xcd_barrier_complete(bar, b.x, nloc, nx); b.st[0] = nloc; b.st[1] = nx; }
.LBB0_571:
	s_or_b64 exec, exec, s[0:1]
	s_mov_b32 s0, 0
	s_getreg_b32 s2, hwreg(HW_REG_XCC_ID, 0, 4)
	s_waitcnt vmcnt(0)
	s_barrier
	s_mov_b64 s[4:5], exec
	v_readlane_b32 s6, v251, 5
	v_readlane_b32 s7, v251, 6
	s_and_b64 s[6:7], s[4:5], s[6:7]
	s_mov_b64 exec, s[6:7]
	s_cbranch_execz .LBB0_623
	s_ashr_i32 s1, s0, 31
	v_readlane_b32 s6, v251, 3
	v_readlane_b32 s7, v251, 4
	s_add_u32 s0, s6, s0
	s_addc_u32 s1, s7, s1
	v_mov_b32_e32 v0, 0x20800
	s_load_dwordx2 s[0:1], s[0:1], 0xf8
	s_waitcnt vmcnt(0) expcnt(0) lgkmcnt(0)
	v_mov_b32_e32 v2, v252
	v_mov_b32_e32 v0, 0x20804
	v_mov_b32_e32 v0, v253
	s_and_b32 s33, s2, 15
	s_waitcnt lgkmcnt(1)
	v_cmp_ne_u32_e32 vcc, 0, v2
	s_cbranch_vccnz .LBB0_587
	s_add_u32 s2, s0, 0x16a4300
	s_addc_u32 s3, s1, 0
	s_add_u32 s6, s0, 0x16a4500
	s_addc_u32 s7, s1, 0
	s_add_u32 s8, s0, 0x16a4600
	s_addc_u32 s9, s1, 0
	s_add_u32 s10, s0, 0x16a4700
	s_addc_u32 s11, s1, 0
	s_add_u32 s12, s0, 0x16a4800
	s_addc_u32 s13, s1, 0
	s_add_u32 s14, s0, 0x16a4900
	s_addc_u32 s15, s1, 0
	s_add_u32 s16, s0, 0x16a4a00
	s_addc_u32 s17, s1, 0
	s_add_u32 s18, s0, 0x16a4b00
	s_addc_u32 s19, s1, 0
	s_add_u32 s20, s0, 0x16a4c00
	s_addc_u32 s21, s1, 0
	s_add_u32 s22, s0, 0x16a4d00
	s_addc_u32 s23, s1, 0
	s_add_u32 s24, s0, 0x16a4e00
	s_addc_u32 s25, s1, 0
	s_add_u32 s26, s0, 0x16a4f00
	s_addc_u32 s27, s1, 0
	s_add_u32 s28, s0, 0x16a5000
	s_addc_u32 s29, s1, 0
	s_add_u32 s30, s0, 0x16a5100
	s_addc_u32 s31, s1, 0
	s_add_u32 s34, s0, 0x16a5200
	s_addc_u32 s35, s1, 0
	s_add_u32 s36, s0, 0x16a5300
	s_addc_u32 s37, s1, 0
	s_add_u32 s38, s0, 0x16a5400
	s_addc_u32 s39, s1, 0
	s_mov_b32 s46, 1
	v_mov_b32_e32 v16, 0
	s_branch .LBB0_575

; #define VBID ((int)(blockIdx.x * 2 + (otid() >> 8)))
; #define LAS __attribute__((address_space(3)))
; template <class FA, class FB, class FL, class FS>
; DI void gemm_tile(char* lds, int ksteps, int rot, FA fa, FB fb, FL fl, FS fs) {
;     ...
; #pragma unroll
;   for (int i = 0; i < 4; ++i) {
;     const int id = tid + i * 256, r = id >> 3, c = (id & 7) ^ (r & 7);
;     __builtin_amdgcn_global_load_lds((const unsigned*)fa(r, rot * 8 + c), (LAS unsigned*)(l3 + id * 16), 16, 0, 0);
;     __builtin_amdgcn_global_load_lds((const unsigned*)fb(r, rot * 8 + c), (LAS unsigned*)(l3 + 16384 + id * 16), 16, 0, 0);
;   }
;   asm volatile("s_waitcnt vmcnt(0)" ::: "memory");
;   __syncthreads();
; DI void phase_s5_y(const Params& p, char* lds) {
;     ...
;   for (int k_ = 0; k_ * VGRID < (nt); ++k_) {
;     int L = k_ * VGRID + VBID; const bool active_ = L < (nt); if (!active_) L = (nt) - 1;
;     const int j = 3 - (L >> 10), rem = L & 1023, g = rem >> 4, mt = rem & 15;
;     const bf16_t* Ug = ugm + (size_t)g * MP * 16 + (size_t)mt * 128 * 512;
;     const bf16_t* Hg = H + ((size_t)g * 2048 + mt * 128) * 128;
;     gemm_tile(lds, 2 + 2 * (j + 1), 0,
;       [&](int r, int kc) { return kc < 16 ? Hg + (size_t)r * 128 + kc * 8 : Ug + (size_t)r * 512 + (kc - 16) * 8; },
;       [&](int n, int kc) {
;         const int nn = j * 128 + n;
;         if (kc < 16) return MC + ((size_t)g * 512 + nn) * 128 + kc * 8;
;         const int t = nn >> 4, co = nn & 15, kk = (kc - 16) * 8, s = kk >> 4, ci0 = kk & 15;
;         if (s > t) return zblk;
;         return KT + ((size_t)(g * 16 + co) * 32 + (t - s)) * 16 + ci0;
;       },
.LBB0_625:
	v_mov_b32_e32 v0, v182
	v_readlane_b32 s1, v251, 7
	v_ashrrev_i32_e32 v0, 8, v0
	s_add_i32 s0, s0, s1
	v_add_u32_e32 v0, s0, v0
	v_min_i32_e32 v0, 0xfff, v0
	v_and_b32_e32 v70, 0x600, v0
	v_and_b32_e32 v71, 0x800, v0
	v_and_b32_e32 v0, 0x1ff, v0
	v_lshl_or_b32 v0, v70, 1, v0
	v_lshrrev_b32_e32 v71, 2, v71
	v_or_b32_e32 v0, v0, v71
	v_bfe_u32 v70, v0, 4, 6
	v_and_b32_e32 v71, 15, v0
	v_lshlrev_b32_e32 v68, 19, v70
	v_mov_b32_e32 v26, v182
	v_ashrrev_i32_e32 v154, 10, v0
	v_lshl_add_u64 v[0:1], s[8:9], 0, v[68:69]
	v_lshlrev_b32_e32 v68, 15, v71
	v_lshl_add_u64 v[6:7], v[0:1], 0, v[68:69]
	v_bfe_u32 v24, v26, 3, 5
	v_xor_b32_e32 v0, v24, v26
	v_lshlrev_b32_sdwa v82, v103, v26 dst_sel:DWORD dst_unused:UNUSED_PAD src0_sel:DWORD src1_sel:BYTE_0
	v_lshlrev_b32_e32 v68, 8, v24
	v_lshlrev_b32_e32 v0, 4, v0
	v_add_u32_e32 v56, v102, v82
	v_sub_u32_e32 v91, 3, v154
	v_lshl_add_u64 v[8:9], v[6:7], 0, v[68:69]
	v_and_b32_e32 v68, 0x70, v0
	v_readfirstlane_b32 s0, v56
	v_lshl_add_u64 v[0:1], v[8:9], 0, v[68:69]
	s_mov_b32 m0, s0
	v_lshlrev_b32_e32 v81, 7, v91
	global_load_lds_dwordx4 v[0:1], off
	v_or_b32_e32 v0, v81, v24
	v_mov_b32_e32 v1, v69
	v_lshlrev_b32_e32 v2, 17, v70
	v_mov_b32_e32 v3, v69
	v_lshl_add_u64 v[10:11], s[10:11], 0, v[2:3]
	v_lshlrev_b64 v[2:3], 8, v[0:1]
	v_add_u32_e32 v1, 0x4000, v56
	v_lshl_add_u64 v[22:23], v[10:11], 0, v[2:3]
	v_readfirstlane_b32 s0, v1
	v_or_b32_sdwa v1, v26, s33 dst_sel:DWORD dst_unused:UNUSED_PAD src0_sel:BYTE_0 src1_sel:DWORD
	v_lshl_add_u64 v[2:3], v[22:23], 0, v[68:69]
	s_mov_b32 m0, s0
	v_lshrrev_b32_e32 v155, 3, v1
	global_load_lds_dwordx4 v[2:3], off
	v_xor_b32_e32 v2, v155, v26
	v_lshlrev_b32_e32 v83, 4, v1
	v_lshlrev_b32_e32 v68, 8, v155
	v_lshlrev_b32_e32 v2, 4, v2
	v_add_u32_e32 v1, v102, v83
	v_lshl_add_u64 v[60:61], v[6:7], 0, v[68:69]
	v_and_b32_e32 v68, 0x70, v2
	v_readfirstlane_b32 s0, v1
	v_lshl_add_u64 v[2:3], v[60:61], 0, v[68:69]
	s_mov_b32 m0, s0
	v_lshrrev_b32_e32 v80, 4, v26
	global_load_lds_dwordx4 v[2:3], off
	v_or_b32_e32 v2, v81, v155
	v_mov_b32_e32 v3, v69
	v_lshlrev_b64 v[4:5], 8, v[2:3]
	v_add_u32_e32 v3, 0x4000, v1
	v_lshl_add_u64 v[62:63], v[10:11], 0, v[4:5]
	v_readfirstlane_b32 s0, v3
	v_or_b32_sdwa v3, v26, s34 dst_sel:DWORD dst_unused:UNUSED_PAD src0_sel:BYTE_0 src1_sel:DWORD
	v_lshl_add_u64 v[4:5], v[62:63], 0, v[68:69]
	s_mov_b32 m0, s0
	v_lshrrev_b32_e32 v156, 3, v3
	global_load_lds_dwordx4 v[4:5], off
	v_xor_b32_e32 v4, v156, v26
	v_lshlrev_b32_e32 v84, 4, v3
	v_lshlrev_b32_e32 v68, 8, v156
	v_lshlrev_b32_e32 v4, 4, v4
	v_add_u32_e32 v3, v102, v84
	v_lshl_add_u64 v[64:65], v[6:7], 0, v[68:69]
	v_and_b32_e32 v68, 0x70, v4
	v_readfirstlane_b32 s0, v3
	v_lshl_add_u64 v[4:5], v[64:65], 0, v[68:69]
	s_mov_b32 m0, s0
	v_and_b32_e32 v25, 7, v26
	global_load_lds_dwordx4 v[4:5], off
	v_or_b32_e32 v4, v81, v156
	v_mov_b32_e32 v5, v69
	v_lshlrev_b64 v[12:13], 8, v[4:5]
	v_add_u32_e32 v5, 0x4000, v3
	v_lshl_add_u64 v[76:77], v[10:11], 0, v[12:13]
	v_readfirstlane_b32 s0, v5
	v_or_b32_sdwa v5, v26, s35 dst_sel:DWORD dst_unused:UNUSED_PAD src0_sel:BYTE_0 src1_sel:DWORD
	v_lshl_add_u64 v[12:13], v[76:77], 0, v[68:69]
	s_mov_b32 m0, s0
	v_lshrrev_b32_e32 v157, 3, v5
	global_load_lds_dwordx4 v[12:13], off
	v_xor_b32_e32 v12, v157, v26
	v_lshlrev_b32_e32 v68, 8, v157
	v_lshlrev_b32_e32 v85, 4, v5
	v_lshl_add_u64 v[100:101], v[6:7], 0, v[68:69]
	v_lshlrev_b32_e32 v6, 4, v12
	v_add_u32_e32 v5, v102, v85
	v_and_b32_e32 v68, 0x70, v6
	v_readfirstlane_b32 s0, v5
	v_lshl_add_u64 v[6:7], v[100:101], 0, v[68:69]
	s_mov_b32 m0, s0
	v_and_b32_e32 v79, 15, v26
	global_load_lds_dwordx4 v[6:7], off
	v_or_b32_e32 v6, v81, v157
	v_mov_b32_e32 v7, v69
	v_lshlrev_b64 v[12:13], 8, v[6:7]
	v_add_u32_e32 v7, 0x4000, v5
	v_lshl_add_u64 v[148:149], v[10:11], 0, v[12:13]
	v_readfirstlane_b32 s0, v7
	v_lshl_add_u64 v[10:11], v[148:149], 0, v[68:69]
	s_mov_b32 m0, s0
	v_lshlrev_b32_e32 v68, 21, v70
	global_load_lds_dwordx4 v[10:11], off
	v_lshl_add_u64 v[10:11], s[6:7], 0, v[68:69]
	v_lshlrev_b32_e32 v68, 17, v71
	v_bfe_u32 v7, v26, 4, 2
	v_lshl_add_u64 v[152:153], v[10:11], 0, v[68:69]
	v_bitop3_b32 v10, v80, v25, 3 bitop3:0x6c
	v_bitop3_b32 v7, v7, v25, 4 bitop3:0x36
	v_bfe_u32 v78, v26, 6, 1
	v_bfe_u32 v86, v26, 7, 1
	v_lshlrev_b32_e32 v87, 4, v10
	v_lshlrev_b32_e32 v14, 7, v79
	v_lshlrev_b32_e32 v90, 4, v7
	v_lshlrev_b32_e32 v7, 7, v26
	v_lshl_or_b32 v88, v78, 13, v14
	v_add_u32_e32 v15, v102, v87
	v_lshl_or_b32 v89, v86, 13, v14
	v_lshlrev_b32_e32 v68, 10, v24
	v_and_b32_e32 v7, 0x3c00, v7
	v_bitop3_b32 v158, v24, 7, v26 bitop3:0x48
	v_add_u32_e32 v27, v15, v88
	v_add_u32_e32 v57, v15, v89
	v_lshl_add_u64 v[24:25], v[152:153], 0, v[68:69]
	v_lshl_or_b32 v68, v70, 14, v7
	s_waitcnt vmcnt(0)
	s_waitcnt vmcnt(0) lgkmcnt(0)
	s_barrier
; #define MFMA16(a, b, c) __builtin_amdgcn_mfma_f32_16x16x32_bf16((a), (b), (c), 0, 0, 0)
; #define LAS __attribute__((address_space(3)))
; template <class FA, class FB, class FL, class FS>
; DI void gemm_tile(char* lds, int ksteps, int rot, FA fa, FB fb, FL fl, FS fs) {
;     ...
;   for (int ks = 0; ks < ksteps; ++ks) {
;     const int cur = ks & 1;
;     if (ks + 1 < ksteps) {
;       int kn = ks + 1 + rot; if (kn >= ksteps) kn -= ksteps;
;       LAS char* dst = l3 + (cur ^ 1) * 32768;
; #pragma unroll
;       for (int i = 0; i < 4; ++i) {
;         const int id = tid + i * 256, r = id >> 3, c = (id & 7) ^ (r & 7);
;         __builtin_amdgcn_global_load_lds((const unsigned*)fa(r, kn * 8 + c), (LAS unsigned*)(dst + id * 16), 16, 0, 0);
;         __builtin_amdgcn_global_load_lds((const unsigned*)fb(r, kn * 8 + c), (LAS unsigned*)(dst + 16384 + id * 16), 16, 0, 0);
;       }
;     }
;     const char* A = lds + cur * 32768;
;     const char* B = A + 16384;
; #pragma unroll
;     for (int kk = 0; kk < 2; ++kk) {
;       bf16x8 af[4], bq[4];
; #pragma unroll
;       for (int m = 0; m < 4; ++m) af[m] = ldfrag(A, 128, wr * 64 + m * 16 + fr, kk * 4 + fq);
; #pragma unroll
;       for (int n = 0; n < 4; ++n) bq[n] = ldfrag(B, 128, wc * 64 + n * 16 + fr, kk * 4 + fq);
; #pragma unroll
;       for (int m = 0; m < 4; ++m)
; #pragma unroll
;         for (int n = 0; n < 4; ++n) acc[m][n] = MFMA16(bq[n], af[m], acc[m][n]);
;     }
;     asm volatile("s_waitcnt vmcnt(0)" ::: "memory");
;     __syncthreads();
	ds_read_b128 v[10:13], v27 offset:16384
	ds_read_b128 v[14:17], v57
	ds_read_b128 v[18:21], v27 offset:18432
	v_bitop3_b32 v159, v155, 7, v26 bitop3:0x48
	ds_read_b128 v[28:31], v57 offset:2048
	ds_read_b128 v[32:35], v27 offset:20480
	v_bitop3_b32 v160, v156, 7, v26 bitop3:0x48
	v_bitop3_b32 v161, v157, 7, v26 bitop3:0x48
	ds_read_b128 v[40:43], v27 offset:22528
	v_lshl_add_u64 v[26:27], s[12:13], 0, v[68:69]
	v_lshlrev_b32_e32 v68, 4, v158
	v_add_u32_e32 v7, 0x8000, v56
	v_lshl_add_u64 v[8:9], v[8:9], 0, v[68:69]
	v_readfirstlane_b32 s0, v7
	v_lshl_add_u64 v[8:9], v[8:9], 0, s[16:17]
	s_mov_b32 m0, s0
	v_add_u32_e32 v7, 0xc000, v56
	global_load_lds_dwordx4 v[8:9], off
	v_lshl_add_u64 v[8:9], v[22:23], 0, v[68:69]
	v_readfirstlane_b32 s0, v7
	v_add_u32_e32 v7, 0x8000, v1
	v_lshl_add_u64 v[8:9], v[8:9], 0, s[16:17]
	s_mov_b32 m0, s0
	v_readfirstlane_b32 s0, v7
	v_add_u32_e32 v1, 0xc000, v1
	global_load_lds_dwordx4 v[8:9], off
	s_mov_b32 m0, s0
	v_readfirstlane_b32 s0, v1
	v_add_u32_e32 v1, v102, v90
	v_lshlrev_b32_e32 v68, 4, v159
	v_add_u32_e32 v7, v1, v88
	ds_read_b128 v[52:55], v57 offset:4096
	ds_read_b128 v[124:127], v7 offset:16384
	ds_read_b128 v[56:59], v57 offset:6144
	v_lshl_add_u64 v[8:9], v[60:61], 0, v[68:69]
	v_lshl_add_u64 v[8:9], v[8:9], 0, s[16:17]
	global_load_lds_dwordx4 v[8:9], off
	v_lshl_add_u64 v[8:9], v[62:63], 0, v[68:69]
	v_lshl_add_u64 v[22:23], v[8:9], 0, s[16:17]
	s_mov_b32 m0, s0
	v_add_u32_e32 v1, v1, v89
	global_load_lds_dwordx4 v[22:23], off
	s_waitcnt lgkmcnt(0)
	v_mfma_f32_16x16x32_bf16 v[44:47], v[18:21], v[14:17], 0
	v_lshlrev_b32_e32 v68, 4, v160
	v_add_u32_e32 v22, 0x8000, v3
	v_add_u32_e32 v3, 0xc000, v3
	v_mfma_f32_16x16x32_bf16 v[48:51], v[32:35], v[14:17], 0
	v_readfirstlane_b32 s0, v22
	s_mov_b32 m0, s0
	v_readfirstlane_b32 s0, v3
	v_mfma_f32_16x16x32_bf16 v[92:95], v[18:21], v[28:31], 0
	v_add_u32_e32 v3, 0x8000, v5
	v_lshl_add_u32 v91, v91, 1, 4
	s_mov_b32 s37, -9
	v_mfma_f32_16x16x32_bf16 v[96:99], v[32:35], v[28:31], 0
	s_mov_b32 s38, 0
	s_mov_b32 s39, 0x8000
	v_mfma_f32_16x16x32_bf16 v[108:111], v[18:21], v[52:55], 0
	v_mfma_f32_16x16x32_bf16 v[112:115], v[32:35], v[52:55], 0
	v_mfma_f32_16x16x32_bf16 v[120:123], v[18:21], v[56:59], 0
	ds_read_b128 v[18:21], v1
	ds_read_b128 v[132:135], v7 offset:18432
	v_mfma_f32_16x16x32_bf16 v[128:131], v[32:35], v[56:59], 0
	ds_read_b128 v[32:35], v1 offset:2048
	ds_read_b128 v[140:143], v7 offset:20480
	ds_read_b128 v[144:147], v7 offset:22528
	v_mfma_f32_16x16x32_bf16 v[36:39], v[10:13], v[14:17], 0
	v_mfma_f32_16x16x32_bf16 v[72:75], v[10:13], v[28:31], 0
	v_mfma_f32_16x16x32_bf16 v[104:107], v[10:13], v[52:55], 0
	v_mfma_f32_16x16x32_bf16 v[8:11], v[10:13], v[56:59], 0
	v_lshl_add_u64 v[12:13], v[64:65], 0, v[68:69]
	v_lshl_add_u64 v[12:13], v[12:13], 0, s[16:17]
	global_load_lds_dwordx4 v[12:13], off
	v_lshl_add_u64 v[12:13], v[76:77], 0, v[68:69]
	v_mfma_f32_16x16x32_bf16 v[14:17], v[40:43], v[14:17], 0
	v_lshl_add_u64 v[12:13], v[12:13], 0, s[16:17]
	s_mov_b32 m0, s0
	v_lshlrev_b32_e32 v68, 4, v161
	global_load_lds_dwordx4 v[12:13], off
	v_lshl_add_u64 v[12:13], v[100:101], 0, v[68:69]
	v_readfirstlane_b32 s0, v3
	v_lshl_add_u64 v[12:13], v[12:13], 0, s[16:17]
	s_mov_b32 m0, s0
	v_add_u32_e32 v3, 0xc000, v5
	global_load_lds_dwordx4 v[12:13], off
	v_lshl_add_u64 v[12:13], v[148:149], 0, v[68:69]
	v_readfirstlane_b32 s0, v3
	v_mfma_f32_16x16x32_bf16 v[116:119], v[40:43], v[52:55], 0
	s_mov_b32 m0, s0
	ds_read_b128 v[148:151], v1 offset:6144
	v_lshlrev_b32_e32 v76, 10, v157
	s_waitcnt lgkmcnt(0)
	v_mfma_f32_16x16x32_bf16 v[52:55], v[144:147], v[18:21], v[14:17]
	v_mov_b32_e32 v77, v69
	v_lshlrev_b32_e32 v68, 1, v154
	v_lshl_add_u64 v[76:77], v[152:153], 0, v[76:77]
	v_lshl_add_u64 v[16:17], v[12:13], 0, s[16:17]
	global_load_lds_dwordx4 v[16:17], off
	ds_read_b128 v[12:15], v1 offset:4096
	v_mfma_f32_16x16x32_bf16 v[28:31], v[40:43], v[28:31], 0
	s_waitcnt vmcnt(0)
	v_sub_u32_e32 v100, 0, v68
	s_mov_b64 s[0:1], 0
	v_mfma_f32_16x16x32_bf16 v[136:139], v[40:43], v[56:59], 0
	s_waitcnt lgkmcnt(0)
	s_barrier
	v_mfma_f32_16x16x32_bf16 v[64:67], v[124:127], v[18:21], v[36:39]
	v_mfma_f32_16x16x32_bf16 v[60:63], v[132:135], v[18:21], v[44:47]
	v_mfma_f32_16x16x32_bf16 v[56:59], v[140:143], v[18:21], v[48:51]
	v_mfma_f32_16x16x32_bf16 v[48:51], v[124:127], v[32:35], v[72:75]
	v_mfma_f32_16x16x32_bf16 v[44:47], v[132:135], v[32:35], v[92:95]
	s_nop 1
	v_lshlrev_b32_e32 v72, 10, v155
	v_mov_b32_e32 v73, v69
	v_lshlrev_b32_e32 v74, 10, v156
	v_mfma_f32_16x16x32_bf16 v[40:43], v[140:143], v[32:35], v[96:99]
	v_lshrrev_b32_e32 v92, 4, v0
	v_lshrrev_b32_e32 v93, 4, v2
	v_lshrrev_b32_e32 v94, 4, v4
	v_mfma_f32_16x16x32_bf16 v[36:39], v[144:147], v[32:35], v[28:31]
	v_lshrrev_b32_e32 v95, 4, v6
	v_mov_b32_e32 v75, v69
	v_lshl_add_u64 v[72:73], v[152:153], 0, v[72:73]
	v_mfma_f32_16x16x32_bf16 v[32:35], v[124:127], v[12:15], v[104:107]
	v_lshl_add_u64 v[74:75], v[152:153], 0, v[74:75]
	v_lshlrev_b32_e32 v96, 3, v158
	v_lshlrev_b32_e32 v97, 3, v159
	v_mfma_f32_16x16x32_bf16 v[28:31], v[132:135], v[12:15], v[108:111]
	v_lshlrev_b32_e32 v98, 3, v160
	v_lshlrev_b32_e32 v99, 3, v161
	v_mfma_f32_16x16x32_bf16 v[20:23], v[140:143], v[12:15], v[112:115]
	v_mfma_f32_16x16x32_bf16 v[16:19], v[144:147], v[12:15], v[116:119]
	v_mfma_f32_16x16x32_bf16 v[12:15], v[124:127], v[148:151], v[8:11]
	v_mfma_f32_16x16x32_bf16 v[8:11], v[132:135], v[148:151], v[120:123]
	v_mfma_f32_16x16x32_bf16 v[4:7], v[140:143], v[148:151], v[128:131]
	v_mfma_f32_16x16x32_bf16 v[0:3], v[144:147], v[148:151], v[136:139]
	v_add_u32_e32 v162, v102, v82
	v_add_u32_e32 v163, v102, v83
	v_add_u32_e32 v164, v102, v84
	v_add_u32_e32 v165, v102, v85
	v_readfirstlane_b32 s52, v102
	v_readfirstlane_b32 s48, v162
	v_readfirstlane_b32 s49, v163
	v_readfirstlane_b32 s50, v164
	v_readfirstlane_b32 s51, v165
	s_lshr_b32 s52, s52, 2
	s_mul_i32 s52, s52, 3
	s_sub_u32 s44, 0x20000, s52
	s_mov_b32 s42, 0
	s_mov_b32 s43, 0x8000
	s_branch .LBB0_627
; #define MFMA16(a, b, c) __builtin_amdgcn_mfma_f32_16x16x32_bf16((a), (b), (c), 0, 0, 0)
; #define LAS __attribute__((address_space(3)))
; template <class FA, class FB, class FL, class FS>
; DI void gemm_tile(char* lds, int ksteps, int rot, FA fa, FB fb, FL fl, FS fs) {
;     ...
;   for (int ks = 0; ks < ksteps; ++ks) {
;     const int cur = ks & 1;
;     if (ks + 1 < ksteps) {
;       int kn = ks + 1 + rot; if (kn >= ksteps) kn -= ksteps;
;       LAS char* dst = l3 + (cur ^ 1) * 32768;
; #pragma unroll
;       for (int i = 0; i < 4; ++i) {
;         const int id = tid + i * 256, r = id >> 3, c = (id & 7) ^ (r & 7);
;         __builtin_amdgcn_global_load_lds((const unsigned*)fa(r, kn * 8 + c), (LAS unsigned*)(dst + id * 16), 16, 0, 0);
;         __builtin_amdgcn_global_load_lds((const unsigned*)fb(r, kn * 8 + c), (LAS unsigned*)(dst + 16384 + id * 16), 16, 0, 0);
;       }
;     }
;     const char* A = lds + cur * 32768;
;     const char* B = A + 16384;
; #pragma unroll
;     for (int kk = 0; kk < 2; ++kk) {
;       bf16x8 af[4], bq[4];
; #pragma unroll
;       for (int m = 0; m < 4; ++m) af[m] = ldfrag(A, 128, wr * 64 + m * 16 + fr, kk * 4 + fq);
; #pragma unroll
;       for (int n = 0; n < 4; ++n) bq[n] = ldfrag(B, 128, wc * 64 + n * 16 + fr, kk * 4 + fq);
; #pragma unroll
;       for (int m = 0; m < 4; ++m)
; #pragma unroll
;         for (int n = 0; n < 4; ++n) acc[m][n] = MFMA16(bq[n], af[m], acc[m][n]);
;     }
;     asm volatile("s_waitcnt vmcnt(0)" ::: "memory");
;     __syncthreads();
.LBB0_626:
	v_add_u32_e32 v162, s43, v102
	v_add_u32_e32 v68, s40, v102
	s_mov_b32 s47, s42
	s_mov_b32 s42, s43
	s_mov_b32 s43, s44
	s_mov_b32 s44, s47
	v_add_u32_e32 v101, v68, v87
	v_add_u32_e32 v124, v101, v88
	ds_read_b128 v[104:107], v124 offset:16384
	v_add3_u32 v101, v162, v87, v89
	ds_read_b128 v[108:111], v124 offset:18432
	ds_read_b128 v[112:115], v101
	ds_read_b128 v[116:119], v101 offset:2048
	ds_read_b128 v[120:123], v124 offset:20480
	ds_read_b128 v[124:127], v124 offset:22528
	s_waitcnt lgkmcnt(0)
	v_mfma_f32_16x16x32_bf16 v[60:63], v[108:111], v[112:115], v[60:63]
	v_add_u32_e32 v68, v68, v90
	s_add_i32 s37, s37, 1
	s_add_i32 s39, s39, 0x8000
	v_mfma_f32_16x16x32_bf16 v[64:67], v[104:107], v[112:115], v[64:67]
	s_add_i32 s38, s38, 64
	v_cmp_eq_u32_e32 vcc, s37, v100
	s_or_b64 s[0:1], vcc, s[0:1]
	v_mfma_f32_16x16x32_bf16 v[56:59], v[120:123], v[112:115], v[56:59]
	v_mfma_f32_16x16x32_bf16 v[52:55], v[124:127], v[112:115], v[52:55]
	v_mfma_f32_16x16x32_bf16 v[48:51], v[104:107], v[116:119], v[48:51]
	v_mfma_f32_16x16x32_bf16 v[44:47], v[108:111], v[116:119], v[44:47]
	v_mfma_f32_16x16x32_bf16 v[40:43], v[120:123], v[116:119], v[40:43]
	v_mfma_f32_16x16x32_bf16 v[36:39], v[124:127], v[116:119], v[36:39]
	ds_read_b128 v[112:115], v101 offset:4096
	ds_read_b128 v[116:119], v101 offset:6144
	v_add_u32_e32 v101, v68, v88
	v_add3_u32 v68, v162, v90, v89
	s_waitcnt lgkmcnt(1)
	v_mfma_f32_16x16x32_bf16 v[32:35], v[104:107], v[112:115], v[32:35]
	v_mfma_f32_16x16x32_bf16 v[28:31], v[108:111], v[112:115], v[28:31]
	v_mfma_f32_16x16x32_bf16 v[20:23], v[120:123], v[112:115], v[20:23]
	v_mfma_f32_16x16x32_bf16 v[16:19], v[124:127], v[112:115], v[16:19]
	s_waitcnt lgkmcnt(0)
	v_mfma_f32_16x16x32_bf16 v[12:15], v[104:107], v[116:119], v[12:15]
	ds_read_b128 v[104:107], v101 offset:16384
	v_mfma_f32_16x16x32_bf16 v[8:11], v[108:111], v[116:119], v[8:11]
	v_mfma_f32_16x16x32_bf16 v[4:7], v[120:123], v[116:119], v[4:7]
	v_mfma_f32_16x16x32_bf16 v[0:3], v[124:127], v[116:119], v[0:3]
	ds_read_b128 v[108:111], v101 offset:18432
	ds_read_b128 v[112:115], v68
	ds_read_b128 v[116:119], v68 offset:2048
	ds_read_b128 v[120:123], v101 offset:20480
	ds_read_b128 v[124:127], v101 offset:22528
	s_waitcnt lgkmcnt(3)
	v_mfma_f32_16x16x32_bf16 v[64:67], v[104:107], v[112:115], v[64:67]
	v_mfma_f32_16x16x32_bf16 v[60:63], v[108:111], v[112:115], v[60:63]
	s_waitcnt lgkmcnt(1)
	v_mfma_f32_16x16x32_bf16 v[56:59], v[120:123], v[112:115], v[56:59]
	s_waitcnt lgkmcnt(0)
	v_mfma_f32_16x16x32_bf16 v[52:55], v[124:127], v[112:115], v[52:55]
	v_mfma_f32_16x16x32_bf16 v[48:51], v[104:107], v[116:119], v[48:51]
	v_mfma_f32_16x16x32_bf16 v[44:47], v[108:111], v[116:119], v[44:47]
	v_mfma_f32_16x16x32_bf16 v[40:43], v[120:123], v[116:119], v[40:43]
	v_mfma_f32_16x16x32_bf16 v[36:39], v[124:127], v[116:119], v[36:39]
	ds_read_b128 v[112:115], v68 offset:4096
	ds_read_b128 v[116:119], v68 offset:6144
	s_cmp_lg_u32 s46, 0
	s_cbranch_scc1 .Ls5r_w4
	s_waitcnt vmcnt(0)
	s_branch .Ls5r_wd
.Ls5r_w4:
	s_waitcnt vmcnt(4)
.Ls5r_wd:
	s_waitcnt lgkmcnt(0)
	v_mfma_f32_16x16x32_bf16 v[32:35], v[104:107], v[112:115], v[32:35]
	s_barrier
	v_mfma_f32_16x16x32_bf16 v[28:31], v[108:111], v[112:115], v[28:31]
	v_mfma_f32_16x16x32_bf16 v[20:23], v[120:123], v[112:115], v[20:23]
	v_mfma_f32_16x16x32_bf16 v[16:19], v[124:127], v[112:115], v[16:19]
	v_mfma_f32_16x16x32_bf16 v[12:15], v[104:107], v[116:119], v[12:15]
	v_mfma_f32_16x16x32_bf16 v[8:11], v[108:111], v[116:119], v[8:11]
	v_mfma_f32_16x16x32_bf16 v[4:7], v[120:123], v[116:119], v[4:7]
	v_mfma_f32_16x16x32_bf16 v[0:3], v[124:127], v[116:119], v[0:3]
	s_andn2_b64 exec, exec, s[0:1]
	s_cbranch_execz .LBB0_624
.LBB0_627:
	s_and_b32 s40, s39, 0x8000
	v_readfirstlane_b32 s45, v91
	v_mov_b32_e32 v108, s31
	v_mov_b32_e32 v106, s30
	s_add_i32 s2, s37, 11
	s_mov_b32 s46, 0
	s_cmp_lg_u32 s37, -9
	s_cbranch_scc1 .Ls5r_b
	v_add_u32_e32 v68, s38, v96
	v_lshl_add_u64 v[104:105], v[68:69], 1, v[24:25]
	s_add_i32 m0, s44, s48
	s_nop 0
	global_load_lds_dwordx4 v[104:105], off
	v_add_u32_e32 v68, s38, v97
	v_lshl_add_u64 v[104:105], v[68:69], 1, v[72:73]
	s_add_i32 m0, s44, s49
	s_nop 0
	global_load_lds_dwordx4 v[104:105], off
	v_add_u32_e32 v68, s38, v98
	v_lshl_add_u64 v[104:105], v[68:69], 1, v[74:75]
	s_add_i32 m0, s44, s50
	s_nop 0
	global_load_lds_dwordx4 v[104:105], off
	v_add_u32_e32 v68, s38, v99
	v_lshl_add_u64 v[104:105], v[68:69], 1, v[76:77]
	s_add_i32 m0, s44, s51
	s_nop 0
	global_load_lds_dwordx4 v[104:105], off
; #define LAS __attribute__((address_space(3)))
; template <class FA, class FB, class FL, class FS>
; DI void gemm_tile(char* lds, int ksteps, int rot, FA fa, FB fb, FL fl, FS fs) {
;     ...
;     if (ks + 1 < ksteps) {
;       int kn = ks + 1 + rot; if (kn >= ksteps) kn -= ksteps;
;       LAS char* dst = l3 + (cur ^ 1) * 32768;
; #pragma unroll
;       for (int i = 0; i < 4; ++i) {
;         const int id = tid + i * 256, r = id >> 3, c = (id & 7) ^ (r & 7);
;         __builtin_amdgcn_global_load_lds((const unsigned*)fa(r, kn * 8 + c), (LAS unsigned*)(dst + id * 16), 16, 0, 0);
;         __builtin_amdgcn_global_load_lds((const unsigned*)fb(r, kn * 8 + c), (LAS unsigned*)(dst + 16384 + id * 16), 16, 0, 0);
;       }
;     }
; DI void xcd_barrier(const XcdBarrier& b) {
;   asm volatile("s_waitcnt vmcnt(0)" ::: "memory");
;   __syncthreads();
;   if (threadIdx.x == 0) {
;     unsigned* bar = b.bar;
;     __builtin_amdgcn_s_waitcnt(0);
;     unsigned nloc = b.st[0], nx = b.st[1];
;     if (nloc == 0u) { xcd_barrier_complete(bar, b.x, nloc, nx); b.st[0] = nloc; b.st[1] = nx; }
.Ls5r_b:
	s_cmp_ge_u32 s2, s45
	s_cbranch_scc1 .LBB0_626
	s_xor_b32 s41, s40, 0x8000
	s_add_i32 s41, s41, 0x4000
	v_add_u32_e32 v68, s38, v96
	v_add_u32_e32 v107, 0x80, v68
	v_lshrrev_b32_e32 v68, 4, v68
	v_sub_co_u32_e32 v68, vcc, v92, v68
	v_and_b32_e32 v107, 8, v107
	v_lshlrev_b32_e32 v68, 5, v68
	v_lshl_add_u64 v[104:105], v[26:27], 0, v[68:69]
	v_lshlrev_b32_e32 v68, 1, v107
	v_lshl_add_u64 v[104:105], v[104:105], 0, v[68:69]
	v_cndmask_b32_e32 v105, v105, v108, vcc
	v_cndmask_b32_e32 v104, v104, v106, vcc
	s_add_i32 m0, s41, s48
	s_nop 0
	global_load_lds_dwordx4 v[104:105], off
	v_add_u32_e32 v68, s38, v97
	v_add_u32_e32 v107, 0x80, v68
	v_lshrrev_b32_e32 v68, 4, v68
	v_sub_co_u32_e32 v68, vcc, v93, v68
	v_and_b32_e32 v107, 8, v107
	v_lshlrev_b32_e32 v68, 5, v68
	v_lshl_add_u64 v[104:105], v[26:27], 0, v[68:69]
	v_lshlrev_b32_e32 v68, 1, v107
	v_lshl_add_u64 v[104:105], v[104:105], 0, v[68:69]
	v_cndmask_b32_e32 v105, v105, v108, vcc
	v_cndmask_b32_e32 v104, v104, v106, vcc
	s_add_i32 m0, s41, s49
	s_nop 0
	global_load_lds_dwordx4 v[104:105], off
	v_add_u32_e32 v68, s38, v98
	v_add_u32_e32 v107, 0x80, v68
	v_lshrrev_b32_e32 v68, 4, v68
	v_sub_co_u32_e32 v68, vcc, v94, v68
	v_and_b32_e32 v107, 8, v107
	v_lshlrev_b32_e32 v68, 5, v68
	v_lshl_add_u64 v[104:105], v[26:27], 0, v[68:69]
	v_lshlrev_b32_e32 v68, 1, v107
	v_lshl_add_u64 v[104:105], v[104:105], 0, v[68:69]
	v_cndmask_b32_e32 v105, v105, v108, vcc
	v_cndmask_b32_e32 v104, v104, v106, vcc
	s_add_i32 m0, s41, s50
	s_nop 0
	global_load_lds_dwordx4 v[104:105], off
	v_add_u32_e32 v68, s38, v99
	v_add_u32_e32 v107, 0x80, v68
	v_lshrrev_b32_e32 v68, 4, v68
	v_sub_co_u32_e32 v68, vcc, v95, v68
	v_and_b32_e32 v107, 8, v107
	v_lshlrev_b32_e32 v68, 5, v68
	v_lshl_add_u64 v[104:105], v[26:27], 0, v[68:69]
	v_lshlrev_b32_e32 v68, 1, v107
	v_lshl_add_u64 v[104:105], v[104:105], 0, v[68:69]
	v_cndmask_b32_e32 v105, v105, v108, vcc
	v_cndmask_b32_e32 v104, v104, v106, vcc
	s_add_i32 m0, s41, s51
	s_nop 0
	global_load_lds_dwordx4 v[104:105], off
	s_add_i32 s2, s37, 12
	s_cmp_ge_u32 s2, s45
	s_cbranch_scc1 .LBB0_626
	s_add_i32 s47, s38, 64
	v_add_u32_e32 v68, s47, v96
	v_lshl_add_u64 v[104:105], v[68:69], 1, v[24:25]
	s_add_i32 m0, s42, s48
	s_nop 0
	global_load_lds_dwordx4 v[104:105], off
	v_add_u32_e32 v68, s47, v97
	v_lshl_add_u64 v[104:105], v[68:69], 1, v[72:73]
	s_add_i32 m0, s42, s49
	s_nop 0
	global_load_lds_dwordx4 v[104:105], off
	v_add_u32_e32 v68, s47, v98
	v_lshl_add_u64 v[104:105], v[68:69], 1, v[74:75]
	s_add_i32 m0, s42, s50
	s_nop 0
	global_load_lds_dwordx4 v[104:105], off
	v_add_u32_e32 v68, s47, v99
	v_lshl_add_u64 v[104:105], v[68:69], 1, v[76:77]
	s_add_i32 m0, s42, s51
	s_nop 0
	global_load_lds_dwordx4 v[104:105], off
	s_mov_b32 s46, 1
	s_branch .LBB0_626
.LBB0_629:
	s_mov_b32 s0, 0
	s_getreg_b32 s2, hwreg(HW_REG_XCC_ID, 0, 4)
	s_waitcnt vmcnt(0)
	s_barrier
	s_mov_b64 s[4:5], exec
	v_readlane_b32 s6, v251, 5
	v_readlane_b32 s7, v251, 6
	s_and_b64 s[6:7], s[4:5], s[6:7]
	s_mov_b64 exec, s[6:7]
	s_cbranch_execz .LBB0_681
	s_ashr_i32 s1, s0, 31
	v_readlane_b32 s6, v251, 3
	v_readlane_b32 s7, v251, 4
	s_add_u32 s0, s6, s0
	s_addc_u32 s1, s7, s1
	v_mov_b32_e32 v0, 0x20800
	s_load_dwordx2 s[0:1], s[0:1], 0xf8
	s_waitcnt vmcnt(0) expcnt(0) lgkmcnt(0)
	v_mov_b32_e32 v2, v252
	v_mov_b32_e32 v0, 0x20804
	v_mov_b32_e32 v0, v253
	s_and_b32 s33, s2, 15
	s_waitcnt lgkmcnt(1)
	v_cmp_ne_u32_e32 vcc, 0, v2
	s_cbranch_vccnz .LBB0_645
	s_add_u32 s2, s0, 0x16a4300
	s_addc_u32 s3, s1, 0
	s_add_u32 s6, s0, 0x16a4500
	s_addc_u32 s7, s1, 0
	s_add_u32 s8, s0, 0x16a4600
	s_addc_u32 s9, s1, 0
	s_add_u32 s10, s0, 0x16a4700
	s_addc_u32 s11, s1, 0
	s_add_u32 s12, s0, 0x16a4800
	s_addc_u32 s13, s1, 0
	s_add_u32 s14, s0, 0x16a4900
	s_addc_u32 s15, s1, 0
	s_add_u32 s16, s0, 0x16a4a00
	s_addc_u32 s17, s1, 0
	s_add_u32 s18, s0, 0x16a4b00
	s_addc_u32 s19, s1, 0
	s_add_u32 s20, s0, 0x16a4c00
	s_addc_u32 s21, s1, 0
	s_add_u32 s22, s0, 0x16a4d00
	s_addc_u32 s23, s1, 0
	s_add_u32 s24, s0, 0x16a4e00
	s_addc_u32 s25, s1, 0
	s_add_u32 s26, s0, 0x16a4f00
	s_addc_u32 s27, s1, 0
	s_add_u32 s28, s0, 0x16a5000
	s_addc_u32 s29, s1, 0
	s_add_u32 s30, s0, 0x16a5100
	s_addc_u32 s31, s1, 0
	s_add_u32 s34, s0, 0x16a5200
	s_addc_u32 s35, s1, 0
	s_add_u32 s36, s0, 0x16a5300
	s_addc_u32 s37, s1, 0
	s_add_u32 s38, s0, 0x16a5400
	s_addc_u32 s39, s1, 0
	s_mov_b32 s46, 1
	v_mov_b32_e32 v16, 0
	s_branch .LBB0_633

; DI void xcd_barrier(const XcdBarrier& b) {
;   asm volatile("s_waitcnt vmcnt(0)" ::: "memory");
;   __syncthreads();
;   if (threadIdx.x == 0) {
;     unsigned* bar = b.bar;
;     __builtin_amdgcn_s_waitcnt(0);
;     unsigned nloc = b.st[0], nx = b.st[1];
;     if (nloc == 0u) { xcd_barrier_complete(bar, b.x, nloc, nx); b.st[0] = nloc; b.st[1] = nx; }
.LBB0_690:
	s_getreg_b32 s2, hwreg(HW_REG_XCC_ID, 0, 4)
	s_waitcnt vmcnt(0)
	s_barrier
	s_mov_b64 s[4:5], exec
	v_readlane_b32 s0, v251, 5
	v_readlane_b32 s1, v251, 6
	s_and_b64 s[0:1], s[4:5], s[0:1]
	s_mov_b64 exec, s[0:1]
	s_cbranch_execz .LBB0_742
	s_ashr_i32 s1, s33, 31
	v_readlane_b32 s8, v251, 3
	v_readlane_b32 s9, v251, 4
	s_add_u32 s0, s8, s33
	s_addc_u32 s1, s9, s1
	v_mov_b32_e32 v0, 0x20800
	s_load_dwordx2 s[0:1], s[0:1], 0xf8
	s_waitcnt vmcnt(0) expcnt(0) lgkmcnt(0)
	v_mov_b32_e32 v2, v252
	v_mov_b32_e32 v0, 0x20804
	v_mov_b32_e32 v0, v253
	s_and_b32 s33, s2, 15
	s_waitcnt lgkmcnt(1)
	v_cmp_ne_u32_e32 vcc, 0, v2
	s_cbranch_vccnz .LBB0_706
	s_add_u32 s2, s0, 0x16a4300
	s_addc_u32 s3, s1, 0
	s_add_u32 s8, s0, 0x16a4500
	s_addc_u32 s9, s1, 0
	s_add_u32 s10, s0, 0x16a4600
	s_addc_u32 s11, s1, 0
	s_add_u32 s12, s0, 0x16a4700
	s_addc_u32 s13, s1, 0
	s_add_u32 s14, s0, 0x16a4800
	s_addc_u32 s15, s1, 0
	s_add_u32 s16, s0, 0x16a4900
	s_addc_u32 s17, s1, 0
	s_add_u32 s18, s0, 0x16a4a00
	s_addc_u32 s19, s1, 0
	s_add_u32 s20, s0, 0x16a4b00
	s_addc_u32 s21, s1, 0
	s_add_u32 s22, s0, 0x16a4c00
	s_addc_u32 s23, s1, 0
	s_add_u32 s24, s0, 0x16a4d00
	s_addc_u32 s25, s1, 0
	s_add_u32 s26, s0, 0x16a4e00
	s_addc_u32 s27, s1, 0
	s_add_u32 s28, s0, 0x16a4f00
	s_addc_u32 s29, s1, 0
	s_add_u32 s30, s0, 0x16a5000
	s_addc_u32 s31, s1, 0
	s_add_u32 s34, s0, 0x16a5100
	s_addc_u32 s35, s1, 0
	s_add_u32 s36, s0, 0x16a5200
	s_addc_u32 s37, s1, 0
	s_add_u32 s38, s0, 0x16a5300
	s_addc_u32 s39, s1, 0
	s_add_u32 s40, s0, 0x16a5400
	s_addc_u32 s41, s1, 0
	s_mov_b32 s48, 1
	v_mov_b32_e32 v16, 0
	s_branch .LBB0_694

; DI void xcd_barrier(const XcdBarrier& b) {
;   asm volatile("s_waitcnt vmcnt(0)" ::: "memory");
;   __syncthreads();
;   if (threadIdx.x == 0) {
;     unsigned* bar = b.bar;
;     __builtin_amdgcn_s_waitcnt(0);
;     unsigned nloc = b.st[0], nx = b.st[1];
;     if (nloc == 0u) { xcd_barrier_complete(bar, b.x, nloc, nx); b.st[0] = nloc; b.st[1] = nx; }
.LBB0_751:
	s_getreg_b32 s2, hwreg(HW_REG_XCC_ID, 0, 4)
	s_waitcnt vmcnt(0)
	s_barrier
	s_mov_b64 s[6:7], exec
	v_readlane_b32 s0, v251, 5
	v_readlane_b32 s1, v251, 6
	s_and_b64 s[0:1], s[6:7], s[0:1]
	v_readlane_b32 s25, v251, 8
	s_mov_b64 exec, s[0:1]
	s_cbranch_execz .LBB0_803
	s_ashr_i32 s1, s33, 31
	v_readlane_b32 s4, v251, 3
	v_readlane_b32 s5, v251, 4
	s_add_u32 s0, s4, s33
	s_addc_u32 s1, s5, s1
	v_mov_b32_e32 v0, 0x20800
	s_load_dwordx2 s[0:1], s[0:1], 0xf8
	s_waitcnt vmcnt(0) expcnt(0) lgkmcnt(0)
	v_mov_b32_e32 v2, v252
	v_mov_b32_e32 v0, 0x20804
	v_mov_b32_e32 v0, v253
	s_and_b32 s33, s2, 15
	s_waitcnt lgkmcnt(1)
	v_cmp_ne_u32_e32 vcc, 0, v2
	s_cbranch_vccnz .LBB0_767
	s_add_u32 s2, s0, 0x16a4300
	s_addc_u32 s3, s1, 0
	s_add_u32 s4, s0, 0x16a4500
	s_addc_u32 s5, s1, 0
	s_add_u32 s8, s0, 0x16a4600
	s_addc_u32 s9, s1, 0
	s_add_u32 s10, s0, 0x16a4700
	s_addc_u32 s11, s1, 0
	s_add_u32 s12, s0, 0x16a4800
	s_addc_u32 s13, s1, 0
	s_add_u32 s14, s0, 0x16a4900
	s_addc_u32 s15, s1, 0
	s_add_u32 s16, s0, 0x16a4a00
	s_addc_u32 s17, s1, 0
	s_add_u32 s18, s0, 0x16a4b00
	s_addc_u32 s19, s1, 0
	s_add_u32 s20, s0, 0x16a4c00
	s_addc_u32 s21, s1, 0
	s_add_u32 s22, s0, 0x16a4d00
	s_addc_u32 s23, s1, 0
	s_add_u32 s24, s0, 0x16a4e00
	s_addc_u32 s25, s1, 0
	s_add_u32 s26, s0, 0x16a4f00
	s_addc_u32 s27, s1, 0
	s_add_u32 s28, s0, 0x16a5000
	s_addc_u32 s29, s1, 0
	s_add_u32 s30, s0, 0x16a5100
	s_addc_u32 s31, s1, 0
	s_add_u32 s34, s0, 0x16a5200
	s_addc_u32 s35, s1, 0
	s_add_u32 s36, s0, 0x16a5300
	s_addc_u32 s37, s1, 0
	s_add_u32 s38, s0, 0x16a5400
	s_addc_u32 s39, s1, 0
	s_mov_b32 s46, 1
	v_mov_b32_e32 v16, 0
	s_branch .LBB0_755

; DI void xcd_barrier(const XcdBarrier& b) {
;   asm volatile("s_waitcnt vmcnt(0)" ::: "memory");
;   __syncthreads();
;   if (threadIdx.x == 0) {
;     unsigned* bar = b.bar;
;     __builtin_amdgcn_s_waitcnt(0);
;     unsigned nloc = b.st[0], nx = b.st[1];
;     if (nloc == 0u) { xcd_barrier_complete(bar, b.x, nloc, nx); b.st[0] = nloc; b.st[1] = nx; }
.LBB0_809:
	s_or_b64 exec, exec, s[0:1]
	s_mov_b32 s0, 0
	s_getreg_b32 s2, hwreg(HW_REG_XCC_ID, 0, 4)
	s_waitcnt vmcnt(0)
	s_waitcnt lgkmcnt(0)
	s_barrier
	s_mov_b64 s[6:7], exec
	v_readlane_b32 s4, v251, 5
	v_readlane_b32 s5, v251, 6
	s_and_b64 s[4:5], s[6:7], s[4:5]
	s_mov_b64 exec, s[4:5]
	s_cbranch_execz .LBB0_861
	s_ashr_i32 s1, s0, 31
	v_readlane_b32 s4, v251, 3
	v_readlane_b32 s5, v251, 4
	s_add_u32 s0, s4, s0
	s_addc_u32 s1, s5, s1
	v_mov_b32_e32 v0, 0x20800
	s_load_dwordx2 s[0:1], s[0:1], 0xf8
	s_waitcnt vmcnt(0) expcnt(0) lgkmcnt(0)
	v_mov_b32_e32 v2, v252
	v_mov_b32_e32 v0, 0x20804
	v_mov_b32_e32 v0, v253
	s_and_b32 s33, s2, 15
	s_waitcnt lgkmcnt(1)
	v_cmp_ne_u32_e32 vcc, 0, v2
	s_cbranch_vccnz .LBB0_825
	s_add_u32 s2, s0, 0x16a4300
	s_addc_u32 s3, s1, 0
	s_add_u32 s4, s0, 0x16a4500
	s_addc_u32 s5, s1, 0
	s_add_u32 s8, s0, 0x16a4600
	s_addc_u32 s9, s1, 0
	s_add_u32 s10, s0, 0x16a4700
	s_addc_u32 s11, s1, 0
	s_add_u32 s12, s0, 0x16a4800
	s_addc_u32 s13, s1, 0
	s_add_u32 s14, s0, 0x16a4900
	s_addc_u32 s15, s1, 0
	s_add_u32 s16, s0, 0x16a4a00
	s_addc_u32 s17, s1, 0
	s_add_u32 s18, s0, 0x16a4b00
	s_addc_u32 s19, s1, 0
	s_add_u32 s20, s0, 0x16a4c00
	s_addc_u32 s21, s1, 0
	s_add_u32 s22, s0, 0x16a4d00
	s_addc_u32 s23, s1, 0
	s_add_u32 s24, s0, 0x16a4e00
	s_addc_u32 s25, s1, 0
	s_add_u32 s26, s0, 0x16a4f00
	s_addc_u32 s27, s1, 0
	s_add_u32 s28, s0, 0x16a5000
	s_addc_u32 s29, s1, 0
	s_add_u32 s30, s0, 0x16a5100
	s_addc_u32 s31, s1, 0
	s_add_u32 s34, s0, 0x16a5200
	s_addc_u32 s35, s1, 0
	s_add_u32 s36, s0, 0x16a5300
	s_addc_u32 s37, s1, 0
	s_add_u32 s38, s0, 0x16a5400
	s_addc_u32 s39, s1, 0
	s_mov_b32 s46, 1
	v_mov_b32_e32 v16, 0
	s_branch .LBB0_813

; DI void xcd_barrier(const XcdBarrier& b) {
;   asm volatile("s_waitcnt vmcnt(0)" ::: "memory");
;   __syncthreads();
;   if (threadIdx.x == 0) {
;     unsigned* bar = b.bar;
;     __builtin_amdgcn_s_waitcnt(0);
;     unsigned nloc = b.st[0], nx = b.st[1];
;     if (nloc == 0u) { xcd_barrier_complete(bar, b.x, nloc, nx); b.st[0] = nloc; b.st[1] = nx; }
.LBB0_1180:
	s_mov_b32 s0, 0
	s_getreg_b32 s2, hwreg(HW_REG_XCC_ID, 0, 4)
	s_waitcnt vmcnt(0)
	s_barrier
	s_mov_b64 s[6:7], exec
	v_readlane_b32 s4, v251, 5
	v_readlane_b32 s5, v251, 6
	s_and_b64 s[4:5], s[6:7], s[4:5]
	s_mov_b64 exec, s[4:5]
	s_cbranch_execz .LBB0_1232
	s_ashr_i32 s1, s0, 31
	v_readlane_b32 s4, v251, 3
	v_readlane_b32 s5, v251, 4
	s_add_u32 s0, s4, s0
	s_addc_u32 s1, s5, s1
	v_mov_b32_e32 v0, 0x20800
	s_load_dwordx2 s[0:1], s[0:1], 0xf8
	s_waitcnt vmcnt(0) expcnt(0) lgkmcnt(0)
	v_mov_b32_e32 v2, v252
	v_mov_b32_e32 v0, 0x20804
	v_mov_b32_e32 v0, v253
	s_and_b32 s33, s2, 15
	s_waitcnt lgkmcnt(1)
	v_cmp_ne_u32_e32 vcc, 0, v2
	s_cbranch_vccnz .LBB0_1196
	s_add_u32 s2, s0, 0x16a4300
	s_addc_u32 s3, s1, 0
	s_add_u32 s4, s0, 0x16a4500
	s_addc_u32 s5, s1, 0
	s_add_u32 s8, s0, 0x16a4600
	s_addc_u32 s9, s1, 0
	s_add_u32 s10, s0, 0x16a4700
	s_addc_u32 s11, s1, 0
	s_add_u32 s12, s0, 0x16a4800
	s_addc_u32 s13, s1, 0
	s_add_u32 s14, s0, 0x16a4900
	s_addc_u32 s15, s1, 0
	s_add_u32 s16, s0, 0x16a4a00
	s_addc_u32 s17, s1, 0
	s_add_u32 s18, s0, 0x16a4b00
	s_addc_u32 s19, s1, 0
	s_add_u32 s20, s0, 0x16a4c00
	s_addc_u32 s21, s1, 0
	s_add_u32 s22, s0, 0x16a4d00
	s_addc_u32 s23, s1, 0
	s_add_u32 s24, s0, 0x16a4e00
	s_addc_u32 s25, s1, 0
	s_add_u32 s26, s0, 0x16a4f00
	s_addc_u32 s27, s1, 0
	s_add_u32 s28, s0, 0x16a5000
	s_addc_u32 s29, s1, 0
	s_add_u32 s30, s0, 0x16a5100
	s_addc_u32 s31, s1, 0
	s_add_u32 s34, s0, 0x16a5200
	s_addc_u32 s35, s1, 0
	s_add_u32 s36, s0, 0x16a5300
	s_addc_u32 s37, s1, 0
	s_add_u32 s38, s0, 0x16a5400
	s_addc_u32 s39, s1, 0
	s_mov_b32 s46, 1
	v_mov_b32_e32 v16, 0
	s_branch .LBB0_1184

; DI void xcd_barrier(const XcdBarrier& b) {
;   asm volatile("s_waitcnt vmcnt(0)" ::: "memory");
;   __syncthreads();
;   if (threadIdx.x == 0) {
;     unsigned* bar = b.bar;
;     __builtin_amdgcn_s_waitcnt(0);
;     unsigned nloc = b.st[0], nx = b.st[1];
;     if (nloc == 0u) { xcd_barrier_complete(bar, b.x, nloc, nx); b.st[0] = nloc; b.st[1] = nx; }
.LBB0_1977:
	s_mov_b32 s0, 0
	s_getreg_b32 s2, hwreg(HW_REG_XCC_ID, 0, 4)
	s_waitcnt vmcnt(0)
	s_barrier
	s_mov_b64 s[6:7], exec
	v_readlane_b32 s4, v251, 5
	v_readlane_b32 s5, v251, 6
	s_and_b64 s[4:5], s[6:7], s[4:5]
	v_readlane_b32 s25, v251, 8
	s_mov_b64 exec, s[4:5]
	s_cbranch_execz .LBB0_2029
	s_ashr_i32 s1, s0, 31
	v_readlane_b32 s4, v251, 3
	v_readlane_b32 s5, v251, 4
	s_add_u32 s0, s4, s0
	s_addc_u32 s1, s5, s1
	v_mov_b32_e32 v0, 0x20800
	s_load_dwordx2 s[0:1], s[0:1], 0xf8
	s_waitcnt vmcnt(0) expcnt(0) lgkmcnt(0)
	v_mov_b32_e32 v2, v252
	v_mov_b32_e32 v0, 0x20804
	v_mov_b32_e32 v0, v253
	s_and_b32 s33, s2, 15
	s_waitcnt lgkmcnt(1)
	v_cmp_ne_u32_e32 vcc, 0, v2
	s_cbranch_vccnz .LBB0_1993
	s_add_u32 s2, s0, 0x16a4300
	s_addc_u32 s3, s1, 0
	s_add_u32 s4, s0, 0x16a4500
	s_addc_u32 s5, s1, 0
	s_add_u32 s8, s0, 0x16a4600
	s_addc_u32 s9, s1, 0
	s_add_u32 s10, s0, 0x16a4700
	s_addc_u32 s11, s1, 0
	s_add_u32 s12, s0, 0x16a4800
	s_addc_u32 s13, s1, 0
	s_add_u32 s14, s0, 0x16a4900
	s_addc_u32 s15, s1, 0
	s_add_u32 s16, s0, 0x16a4a00
	s_addc_u32 s17, s1, 0
	s_add_u32 s18, s0, 0x16a4b00
	s_addc_u32 s19, s1, 0
	s_add_u32 s20, s0, 0x16a4c00
	s_addc_u32 s21, s1, 0
	s_add_u32 s22, s0, 0x16a4d00
	s_addc_u32 s23, s1, 0
	s_add_u32 s24, s0, 0x16a4e00
	s_addc_u32 s25, s1, 0
	s_add_u32 s26, s0, 0x16a4f00
	s_addc_u32 s27, s1, 0
	s_add_u32 s28, s0, 0x16a5000
	s_addc_u32 s29, s1, 0
	s_add_u32 s30, s0, 0x16a5100
	s_addc_u32 s31, s1, 0
	s_add_u32 s34, s0, 0x16a5200
	s_addc_u32 s35, s1, 0
	s_add_u32 s36, s0, 0x16a5300
	s_addc_u32 s37, s1, 0
	s_add_u32 s38, s0, 0x16a5400
	s_addc_u32 s39, s1, 0
	s_mov_b32 s46, 1
	v_mov_b32_e32 v16, 0
	s_branch .LBB0_1981

; DI void xcd_barrier(const XcdBarrier& b) {
;   asm volatile("s_waitcnt vmcnt(0)" ::: "memory");
;   __syncthreads();
;   if (threadIdx.x == 0) {
;     unsigned* bar = b.bar;
;     __builtin_amdgcn_s_waitcnt(0);
;     unsigned nloc = b.st[0], nx = b.st[1];
;     if (nloc == 0u) { xcd_barrier_complete(bar, b.x, nloc, nx); b.st[0] = nloc; b.st[1] = nx; }
.LBB0_2034:
	s_or_b64 exec, exec, s[0:1]
	s_mov_b32 s0, 0
	s_getreg_b32 s2, hwreg(HW_REG_XCC_ID, 0, 4)
	s_waitcnt vmcnt(0)
	s_barrier
	s_mov_b64 s[6:7], exec
	v_readlane_b32 s4, v251, 5
	v_readlane_b32 s5, v251, 6
	s_and_b64 s[4:5], s[6:7], s[4:5]
	s_mov_b64 exec, s[4:5]
	s_cbranch_execz .LBB0_2086
	s_ashr_i32 s1, s0, 31
	v_readlane_b32 s4, v251, 3
	v_readlane_b32 s5, v251, 4
	s_add_u32 s0, s4, s0
	s_addc_u32 s1, s5, s1
	v_mov_b32_e32 v0, 0x20800
	s_load_dwordx2 s[0:1], s[0:1], 0xf8
	s_waitcnt vmcnt(0) expcnt(0) lgkmcnt(0)
	v_mov_b32_e32 v2, v252
	v_mov_b32_e32 v0, 0x20804
	v_mov_b32_e32 v0, v253
	s_and_b32 s33, s2, 15
	s_waitcnt lgkmcnt(1)
	v_cmp_ne_u32_e32 vcc, 0, v2
	s_cbranch_vccnz .LBB0_2050
	s_add_u32 s2, s0, 0x16a4300
	s_addc_u32 s3, s1, 0
	s_add_u32 s4, s0, 0x16a4500
	s_addc_u32 s5, s1, 0
	s_add_u32 s8, s0, 0x16a4600
	s_addc_u32 s9, s1, 0
	s_add_u32 s10, s0, 0x16a4700
	s_addc_u32 s11, s1, 0
	s_add_u32 s12, s0, 0x16a4800
	s_addc_u32 s13, s1, 0
	s_add_u32 s14, s0, 0x16a4900
	s_addc_u32 s15, s1, 0
	s_add_u32 s16, s0, 0x16a4a00
	s_addc_u32 s17, s1, 0
	s_add_u32 s18, s0, 0x16a4b00
	s_addc_u32 s19, s1, 0
	s_add_u32 s20, s0, 0x16a4c00
	s_addc_u32 s21, s1, 0
	s_add_u32 s22, s0, 0x16a4d00
	s_addc_u32 s23, s1, 0
	s_add_u32 s24, s0, 0x16a4e00
	s_addc_u32 s25, s1, 0
	s_add_u32 s26, s0, 0x16a4f00
	s_addc_u32 s27, s1, 0
	s_add_u32 s28, s0, 0x16a5000
	s_addc_u32 s29, s1, 0
	s_add_u32 s30, s0, 0x16a5100
	s_addc_u32 s31, s1, 0
	s_add_u32 s34, s0, 0x16a5200
	s_addc_u32 s35, s1, 0
	s_add_u32 s36, s0, 0x16a5300
	s_addc_u32 s37, s1, 0
	s_add_u32 s38, s0, 0x16a5400
	s_addc_u32 s39, s1, 0
	s_mov_b32 s46, 1
	v_mov_b32_e32 v16, 0
	s_branch .LBB0_2038

; DI void xcd_barrier(const XcdBarrier& b) {
;   asm volatile("s_waitcnt vmcnt(0)" ::: "memory");
;   __syncthreads();
;   if (threadIdx.x == 0) {
;     unsigned* bar = b.bar;
;     __builtin_amdgcn_s_waitcnt(0);
;     unsigned nloc = b.st[0], nx = b.st[1];
;     if (nloc == 0u) { xcd_barrier_complete(bar, b.x, nloc, nx); b.st[0] = nloc; b.st[1] = nx; }
.LBB0_2096:
	s_getreg_b32 s4, hwreg(HW_REG_XCC_ID, 0, 4)
	s_waitcnt vmcnt(0)
	s_barrier
	s_mov_b64 s[2:3], exec
	v_readlane_b32 s0, v251, 5
	v_readlane_b32 s1, v251, 6
	s_and_b64 s[0:1], s[2:3], s[0:1]
	s_mov_b64 exec, s[0:1]
	s_cbranch_execz .LBB0_2148
	s_ashr_i32 s1, s33, 31
	v_readlane_b32 s6, v251, 3
	v_readlane_b32 s7, v251, 4
	s_add_u32 s0, s6, s33
	s_addc_u32 s1, s7, s1
	v_mov_b32_e32 v0, 0x20800
	s_load_dwordx2 s[0:1], s[0:1], 0xf8
	s_waitcnt vmcnt(0) expcnt(0) lgkmcnt(0)
	v_mov_b32_e32 v2, v252
	v_mov_b32_e32 v0, 0x20804
	v_mov_b32_e32 v0, v253
	s_and_b32 s33, s4, 15
	s_waitcnt lgkmcnt(1)
	v_cmp_ne_u32_e32 vcc, 0, v2
	s_cbranch_vccnz .LBB0_2112
	s_add_u32 s4, s0, 0x16a4300
	s_addc_u32 s5, s1, 0
	s_add_u32 s6, s0, 0x16a4500
	s_addc_u32 s7, s1, 0
	s_add_u32 s8, s0, 0x16a4600
	s_addc_u32 s9, s1, 0
	s_add_u32 s10, s0, 0x16a4700
	s_addc_u32 s11, s1, 0
	s_add_u32 s12, s0, 0x16a4800
	s_addc_u32 s13, s1, 0
	s_add_u32 s14, s0, 0x16a4900
	s_addc_u32 s15, s1, 0
	s_add_u32 s16, s0, 0x16a4a00
	s_addc_u32 s17, s1, 0
	s_add_u32 s18, s0, 0x16a4b00
	s_addc_u32 s19, s1, 0
	s_add_u32 s20, s0, 0x16a4c00
	s_addc_u32 s21, s1, 0
	s_add_u32 s22, s0, 0x16a4d00
	s_addc_u32 s23, s1, 0
	s_add_u32 s24, s0, 0x16a4e00
	s_addc_u32 s25, s1, 0
	s_add_u32 s26, s0, 0x16a4f00
	s_addc_u32 s27, s1, 0
	s_add_u32 s28, s0, 0x16a5000
	s_addc_u32 s29, s1, 0
	s_add_u32 s30, s0, 0x16a5100
	s_addc_u32 s31, s1, 0
	s_add_u32 s34, s0, 0x16a5200
	s_addc_u32 s35, s1, 0
	s_add_u32 s36, s0, 0x16a5300
	s_addc_u32 s37, s1, 0
	s_add_u32 s38, s0, 0x16a5400
	s_addc_u32 s39, s1, 0
	s_mov_b32 s46, 1
	v_mov_b32_e32 v16, 0
	s_branch .LBB0_2100

; __global__ void __launch_bounds__(512, 1) fwd_megakernel(Params p) {
;   __shared__ __attribute__((aligned(16))) char lds_all[LDS_BYTES];
	.amdhsa_kernel _Z14fwd_megakernel6Params
		.amdhsa_group_segment_fixed_size 163840
		.amdhsa_private_segment_fixed_size 0
		.amdhsa_kernarg_size 512
		.amdhsa_user_sgpr_count 2
		.amdhsa_user_sgpr_dispatch_ptr 0
		.amdhsa_user_sgpr_queue_ptr 0
		.amdhsa_user_sgpr_kernarg_segment_ptr 1
		.amdhsa_user_sgpr_dispatch_id 0
		.amdhsa_user_sgpr_kernarg_preload_length 0
		.amdhsa_user_sgpr_kernarg_preload_offset 0
		.amdhsa_user_sgpr_private_segment_size 0
		.amdhsa_uses_dynamic_stack 0
		.amdhsa_enable_private_segment 0
		.amdhsa_system_sgpr_workgroup_id_x 1
		.amdhsa_system_sgpr_workgroup_id_y 0
		.amdhsa_system_sgpr_workgroup_id_z 0
		.amdhsa_system_sgpr_workgroup_info 0
		.amdhsa_system_vgpr_workitem_id 2
		.amdhsa_next_free_vgpr 256
		.amdhsa_next_free_sgpr 102
		.amdhsa_accum_offset 256
		.amdhsa_reserve_vcc 1
		.amdhsa_float_round_mode_32 0
		.amdhsa_float_round_mode_16_64 0
		.amdhsa_float_denorm_mode_32 3
		.amdhsa_float_denorm_mode_16_64 3
		.amdhsa_dx10_clamp 1
		.amdhsa_ieee_mode 1
		.amdhsa_fp16_overflow 0
		.amdhsa_tg_split 0
		.amdhsa_exception_fp_ieee_invalid_op 0
		.amdhsa_exception_fp_denorm_src 0
		.amdhsa_exception_fp_ieee_div_zero 0
		.amdhsa_exception_fp_ieee_overflow 0
		.amdhsa_exception_fp_ieee_underflow 0
		.amdhsa_exception_fp_ieee_inexact 0
		.amdhsa_exception_int_div_zero 0
	.end_amdhsa_kernel

; __global__ void __launch_bounds__(512, 1) fwd_megakernel(Params p) {
;   __shared__ __attribute__((aligned(16))) char lds_all[LDS_BYTES];
amdhsa.kernels:
  - .agpr_count:     0
    .args:
      - .offset:         0
        .size:           256
        .value_kind:     by_value
      - .offset:         256
        .size:           4
        .value_kind:     hidden_block_count_x
      - .offset:         260
        .size:           4
        .value_kind:     hidden_block_count_y
      - .offset:         264
        .size:           4
        .value_kind:     hidden_block_count_z
      - .offset:         268
        .size:           2
        .value_kind:     hidden_group_size_x
      - .offset:         270
        .size:           2
        .value_kind:     hidden_group_size_y
      - .offset:         272
        .size:           2
        .value_kind:     hidden_group_size_z
      - .offset:         274
        .size:           2
        .value_kind:     hidden_remainder_x
      - .offset:         276
        .size:           2
        .value_kind:     hidden_remainder_y
      - .offset:         278
        .size:           2
        .value_kind:     hidden_remainder_z
      - .offset:         296
        .size:           8
        .value_kind:     hidden_global_offset_x
      - .offset:         304
        .size:           8
        .value_kind:     hidden_global_offset_y
      - .offset:         312
        .size:           8
        .value_kind:     hidden_global_offset_z
      - .offset:         320
        .size:           2
        .value_kind:     hidden_grid_dims
      - .offset:         344
        .size:           8
        .value_kind:     hidden_multigrid_sync_arg
    .group_segment_fixed_size: 163840
    .kernarg_segment_align: 8
    .kernarg_segment_size: 512
    .language:       OpenCL C
    .language_version:
      - 2
      - 0
    .max_flat_workgroup_size: 512
    .name:           _Z14fwd_megakernel6Params
    .private_segment_fixed_size: 0
    .sgpr_count:     108
    .sgpr_spill_count: 266
    .symbol:         _Z14fwd_megakernel6Params.kd
    .uniform_work_group_size: 1
    .uses_dynamic_stack: false
    .vgpr_count:     256
    .vgpr_spill_count: 0
    .wavefront_size: 64
